# phases 3 and 5: s_waitcnt lgkmcnt that followed the former ds_bpermute sums removed (DPP moves need none)
# baseline (speedup 1.0000x reference)
; DI unsigned pk2(float a, float b) { f32x2 v = {a, b}; bf16x2_t r = __builtin_convertvector(v, bf16x2_t); return __builtin_bit_cast(unsigned, r); }
; DI float bflo(unsigned u) { return __uint_as_float(u << 16); }
; DI float bfhi(unsigned u) { return __uint_as_float(u & 0xffff0000u); }
; DI float siluf_(float x) { return x * __builtin_amdgcn_rcpf(1.f + __expf(-x)); }
; DI void dn_conv_phase(const Params& p) {
;     ...
;         for (int q = 0; q < SEG + 4; ++q) { const int t = t0 + q - 2; rows[q] = (t >= 0 && t < L) ? *(const u32x4*)(src + (ptrdiff_t)(q - 2) * P1W) : zero; }
;         f32x2 ring[5][4];
; #pragma unroll
;         for (int q = 0; q < 4; ++q) { const u32x4 u = rows[q];
;             ring[q][0] = (f32x2){bflo(u.x), bfhi(u.x)}; ring[q][1] = (f32x2){bflo(u.y), bfhi(u.y)}; ring[q][2] = (f32x2){bflo(u.z), bfhi(u.z)}; ring[q][3] = (f32x2){bflo(u.w), bfhi(u.w)}; }
; #pragma unroll
;         for (int tt = 0; tt < SEG; ++tt) {
;             { const u32x4 u = rows[tt + 4]; const int sl = (tt + 4) % 5;
;               ring[sl][0] = (f32x2){bflo(u.x), bfhi(u.x)}; ring[sl][1] = (f32x2){bflo(u.y), bfhi(u.y)}; ring[sl][2] = (f32x2){bflo(u.z), bfhi(u.z)}; ring[sl][3] = (f32x2){bflo(u.w), bfhi(u.w)}; }
;             f32x2 o2[4];
; #pragma unroll
;             for (int e = 0; e < 4; ++e) o2[e] = w[0][e] * ring[tt % 5][e];
; #pragma unroll
;             for (int j = 1; j < 5; ++j)
; #pragma unroll
;                 for (int e = 0; e < 4; ++e) o2[e] += w[j][e] * ring[(tt + j) % 5][e];
;             float o[8];
; #pragma unroll
;             for (int e = 0; e < 4; ++e) { o[2 * e] = siluf_(o2[e].x); o[2 * e + 1] = siluf_(o2[e].y); }
;             if (part < 2) {
;                 float ss = 0.f;
; #pragma unroll
;                 for (int e = 0; e < 8; ++e) ss += o[e] * o[e];
;                 ss += __shfl_xor(ss, 1); ss += __shfl_xor(ss, 2); ss += __shfl_xor(ss, 4); ss += __shfl_xor(ss, 8);
;                 const float sc = rsqrtf(ss + EPS) * (part == 0 ? 0.08838834764831845f : 1.f);
; #pragma unroll
;                 for (int e = 0; e < 8; ++e) o[e] *= sc;
;             }
;             u32x4 ov; ov.x = pk2(o[0], o[1]); ov.y = pk2(o[2], o[3]); ov.z = pk2(o[4], o[5]); ov.w = pk2(o[6], o[7]);
;             *(u32x4*)(QKV + (size_t)(row0 + tt) * 1536 + ch) = ov;
.LBB0_311:
	s_or_b64 exec, exec, s[4:5]
	s_waitcnt vmcnt(0)
	v_lshlrev_b32_e32 v152, 16, v100
	v_and_b32_e32 v153, 0xffff0000, v100
	v_lshlrev_b32_e32 v150, 16, v101
	v_and_b32_e32 v151, 0xffff0000, v101
	v_lshlrev_b32_e32 v138, 16, v102
	v_and_b32_e32 v139, 0xffff0000, v102
	v_lshlrev_b32_e32 v136, 16, v103
	v_and_b32_e32 v137, 0xffff0000, v103
	v_mad_u64_u32 v[140:141], s[4:5], v130, -3, v[120:121]
	v_lshlrev_b32_e32 v142, 16, v104
	v_and_b32_e32 v143, 0xffff0000, v104
	v_lshlrev_b32_e32 v144, 16, v105
	v_and_b32_e32 v145, 0xffff0000, v105
	v_lshlrev_b32_e32 v158, 16, v106
	v_and_b32_e32 v159, 0xffff0000, v106
	v_lshlrev_b32_e32 v160, 16, v107
	v_and_b32_e32 v161, 0xffff0000, v107
	v_lshlrev_b32_e32 v148, 16, v108
	v_and_b32_e32 v149, 0xffff0000, v108
	v_lshlrev_b32_e32 v134, 16, v109
	v_and_b32_e32 v135, 0xffff0000, v109
	v_lshlrev_b32_e32 v132, 16, v110
	v_and_b32_e32 v133, 0xffff0000, v110
	v_lshlrev_b32_e32 v130, 16, v111
	v_and_b32_e32 v131, 0xffff0000, v111
	v_lshlrev_b32_e32 v146, 16, v112
	v_and_b32_e32 v147, 0xffff0000, v112
	v_lshlrev_b32_e32 v128, 16, v113
	v_and_b32_e32 v129, 0xffff0000, v113
	v_lshlrev_b32_e32 v112, 16, v114
	v_and_b32_e32 v113, 0xffff0000, v114
	v_lshlrev_b32_e32 v110, 16, v115
	v_and_b32_e32 v111, 0xffff0000, v115
	v_lshlrev_b32_e32 v108, 16, v116
	v_and_b32_e32 v109, 0xffff0000, v116
	v_lshlrev_b32_e32 v106, 16, v117
	v_and_b32_e32 v107, 0xffff0000, v117
	v_lshlrev_b32_e32 v104, 16, v118
	v_and_b32_e32 v105, 0xffff0000, v118
	v_lshlrev_b32_e32 v102, 16, v119
	v_and_b32_e32 v103, 0xffff0000, v119
	v_pk_mul_f32 v[100:101], v[20:21], v[152:153]
	v_pk_mul_f32 v[114:115], v[22:23], v[150:151]
	v_pk_mul_f32 v[116:117], v[12:13], v[138:139]
	v_pk_mul_f32 v[118:119], v[14:15], v[136:137]
	v_pk_fma_f32 v[100:101], v[4:5], v[142:143], v[100:101]
	v_pk_fma_f32 v[114:115], v[6:7], v[144:145], v[114:115]
	v_pk_fma_f32 v[116:117], v[0:1], v[158:159], v[116:117]
	v_pk_fma_f32 v[118:119], v[2:3], v[160:161], v[118:119]
	v_pk_fma_f32 v[100:101], v[24:25], v[148:149], v[100:101]
	v_pk_fma_f32 v[114:115], v[26:27], v[134:135], v[114:115]
	v_pk_fma_f32 v[116:117], v[16:17], v[132:133], v[116:117]
	v_pk_fma_f32 v[118:119], v[18:19], v[130:131], v[118:119]
	v_pk_fma_f32 v[100:101], v[36:37], v[146:147], v[100:101]
	v_pk_fma_f32 v[114:115], v[38:39], v[128:129], v[114:115]
	v_pk_fma_f32 v[116:117], v[28:29], v[112:113], v[116:117]
	v_pk_fma_f32 v[118:119], v[30:31], v[110:111], v[118:119]
	v_cmp_gt_i32_e32 vcc, 2, v140
	v_cmp_eq_u32_e64 s[4:5], 0, v140
	v_pk_fma_f32 v[100:101], v[32:33], v[108:109], v[100:101]
	v_pk_fma_f32 v[140:141], v[34:35], v[106:107], v[114:115]
	v_pk_fma_f32 v[142:143], v[8:9], v[104:105], v[116:117]
	v_pk_fma_f32 v[144:145], v[10:11], v[102:103], v[118:119]
	v_mul_f32_e32 v114, 0xbfb8aa3b, v100
	v_mul_f32_e32 v115, 0xbfb8aa3b, v101
	v_mul_f32_e32 v116, 0xbfb8aa3b, v140
	v_mul_f32_e32 v117, 0xbfb8aa3b, v141
	v_mul_f32_e32 v118, 0xbfb8aa3b, v142
	v_mul_f32_e32 v119, 0xbfb8aa3b, v143
	v_mul_f32_e32 v158, 0xbfb8aa3b, v144
	v_mul_f32_e32 v159, 0xbfb8aa3b, v145
	v_exp_f32_e32 v114, v114
	v_exp_f32_e32 v115, v115
	v_exp_f32_e32 v116, v116
	v_exp_f32_e32 v117, v117
	v_exp_f32_e32 v118, v118
	v_exp_f32_e32 v119, v119
	v_exp_f32_e32 v158, v158
	v_exp_f32_e32 v159, v159
	v_add_f32_e32 v114, 1.0, v114
	v_add_f32_e32 v115, 1.0, v115
	v_add_f32_e32 v116, 1.0, v116
	v_add_f32_e32 v117, 1.0, v117
	v_add_f32_e32 v118, 1.0, v118
	v_add_f32_e32 v119, 1.0, v119
	v_add_f32_e32 v158, 1.0, v158
	v_add_f32_e32 v159, 1.0, v159
	v_rcp_f32_e32 v114, v114
	v_rcp_f32_e32 v115, v115
	v_rcp_f32_e32 v116, v116
	v_rcp_f32_e32 v117, v117
	v_rcp_f32_e32 v118, v118
	v_rcp_f32_e32 v119, v119
	v_rcp_f32_e32 v158, v158
	v_rcp_f32_e32 v159, v159
	v_cndmask_b32_e64 v157, 1.0, v154, s[4:5]
	v_pk_mul_f32 v[114:115], v[100:101], v[114:115]
	v_pk_mul_f32 v[116:117], v[140:141], v[116:117]
	v_pk_mul_f32 v[118:119], v[142:143], v[118:119]
	v_pk_mul_f32 v[140:141], v[144:145], v[158:159]
	v_mbcnt_hi_u32_b32 v158, -1, v155
	s_and_saveexec_b64 s[24:25], vcc
	s_cbranch_execz .LBB0_313
	v_pk_mul_f32 v[100:101], v[114:115], v[114:115]
	v_pk_mul_f32 v[142:143], v[116:117], v[116:117]
	v_add_f32_e32 v100, v100, v101
	v_add_f32_e32 v100, v142, v100
	v_pk_mul_f32 v[144:145], v[118:119], v[118:119]
	v_add_f32_e32 v100, v143, v100
	v_and_b32_e32 v142, 64, v158
	v_add_f32_e32 v100, v144, v100
	v_xor_b32_e32 v101, 1, v158
	v_add_u32_e32 v142, 64, v142
	v_pk_mul_f32 v[160:161], v[140:141], v[140:141]
	v_add_f32_e32 v100, v145, v100
	v_cmp_lt_i32_e64 s[4:5], v101, v142
	v_add_f32_e32 v100, v160, v100
	v_add_f32_e32 v100, v161, v100
	v_cndmask_b32_e64 v101, v158, v101, s[4:5]
	v_lshlrev_b32_e32 v101, 2, v101
	s_nop 1
	v_mov_b32_dpp v101, v100 quad_perm:[1,0,3,2] row_mask:0xf bank_mask:0xf
	v_add_f32_e32 v100, v100, v101
	v_xor_b32_e32 v101, 2, v158
	v_cmp_lt_i32_e64 s[4:5], v101, v142
	s_nop 1
	v_cndmask_b32_e64 v101, v158, v101, s[4:5]
	v_lshlrev_b32_e32 v101, 2, v101
	s_nop 1
	v_mov_b32_dpp v101, v100 quad_perm:[2,3,0,1] row_mask:0xf bank_mask:0xf
	v_add_f32_e32 v100, v100, v101
	v_xor_b32_e32 v101, 4, v158
	v_cmp_lt_i32_e64 s[4:5], v101, v142
	s_nop 1
	v_cndmask_b32_e64 v101, v158, v101, s[4:5]
	v_lshlrev_b32_e32 v101, 2, v101
	s_nop 1
	v_mov_b32_dpp v101, v100 row_half_mirror row_mask:0xf bank_mask:0xf
	v_add_f32_e32 v100, v100, v101
	v_xor_b32_e32 v101, 8, v158
	v_cmp_lt_i32_e64 s[4:5], v101, v142
	s_nop 1
	v_cndmask_b32_e64 v101, v158, v101, s[4:5]
	v_lshlrev_b32_e32 v101, 2, v101
	s_nop 1
	v_mov_b32_dpp v101, v100 row_ror:8 row_mask:0xf bank_mask:0xf
	v_add_f32_e32 v100, v100, v101
	v_add_f32_e32 v100, 0x358637bd, v100
	v_mul_f32_e32 v101, 0x4b800000, v100
	v_cmp_gt_f32_e64 s[4:5], s46, v100
	s_nop 1
	v_cndmask_b32_e64 v100, v100, v101, s[4:5]
	v_rsq_f32_e32 v100, v100
	s_nop 0
	v_mul_f32_e32 v101, 0x45800000, v100
	v_cndmask_b32_e64 v100, v100, v101, s[4:5]
	v_mul_f32_e32 v100, v157, v100
	v_pk_mul_f32 v[140:141], v[140:141], v[100:101] op_sel_hi:[1,0]
	v_pk_mul_f32 v[118:119], v[118:119], v[100:101] op_sel_hi:[1,0]
	v_pk_mul_f32 v[116:117], v[116:117], v[100:101] op_sel_hi:[1,0]
	v_pk_mul_f32 v[114:115], v[114:115], v[100:101] op_sel_hi:[1,0]
; DI unsigned pk2(float a, float b) { f32x2 v = {a, b}; bf16x2_t r = __builtin_convertvector(v, bf16x2_t); return __builtin_bit_cast(unsigned, r); }
; DI float bflo(unsigned u) { return __uint_as_float(u << 16); }
; DI float bfhi(unsigned u) { return __uint_as_float(u & 0xffff0000u); }
; DI float siluf_(float x) { return x * __builtin_amdgcn_rcpf(1.f + __expf(-x)); }
; DI void dn_conv_phase(const Params& p) {
;     ...
;         for (int tt = 0; tt < SEG; ++tt) {
;             { const u32x4 u = rows[tt + 4]; const int sl = (tt + 4) % 5;
;               ring[sl][0] = (f32x2){bflo(u.x), bfhi(u.x)}; ring[sl][1] = (f32x2){bflo(u.y), bfhi(u.y)}; ring[sl][2] = (f32x2){bflo(u.z), bfhi(u.z)}; ring[sl][3] = (f32x2){bflo(u.w), bfhi(u.w)}; }
;             f32x2 o2[4];
; #pragma unroll
;             for (int e = 0; e < 4; ++e) o2[e] = w[0][e] * ring[tt % 5][e];
; #pragma unroll
;             for (int j = 1; j < 5; ++j)
; #pragma unroll
;                 for (int e = 0; e < 4; ++e) o2[e] += w[j][e] * ring[(tt + j) % 5][e];
;             float o[8];
; #pragma unroll
;             for (int e = 0; e < 4; ++e) { o[2 * e] = siluf_(o2[e].x); o[2 * e + 1] = siluf_(o2[e].y); }
;             if (part < 2) {
;                 float ss = 0.f;
; #pragma unroll
;                 for (int e = 0; e < 8; ++e) ss += o[e] * o[e];
;                 ss += __shfl_xor(ss, 1); ss += __shfl_xor(ss, 2); ss += __shfl_xor(ss, 4); ss += __shfl_xor(ss, 8);
;                 const float sc = rsqrtf(ss + EPS) * (part == 0 ? 0.08838834764831845f : 1.f);
; #pragma unroll
;                 for (int e = 0; e < 8; ++e) o[e] *= sc;
;             }
;             u32x4 ov; ov.x = pk2(o[0], o[1]); ov.y = pk2(o[2], o[3]); ov.z = pk2(o[4], o[5]); ov.w = pk2(o[6], o[7]);
;             *(u32x4*)(QKV + (size_t)(row0 + tt) * 1536 + ch) = ov;
.LBB0_313:
	s_or_b64 exec, exec, s[24:25]
	v_mad_i64_i32 v[142:143], s[4:5], v156, s45, 0
	v_lshl_add_u64 v[100:101], v[126:127], 1, s[28:29]
	v_cvt_pk_bf16_f32 v114, v114, v115
	v_cvt_pk_bf16_f32 v115, v116, v117
	v_cvt_pk_bf16_f32 v116, v118, v119
	v_cvt_pk_bf16_f32 v117, v140, v141
	v_lshl_add_u64 v[118:119], v[100:101], 0, v[142:143]
	global_store_dwordx4 v[118:119], v[114:117], off
	v_lshlrev_b32_e32 v144, 16, v96
	v_and_b32_e32 v145, 0xffff0000, v96
	v_lshlrev_b32_e32 v142, 16, v97
	v_and_b32_e32 v143, 0xffff0000, v97
	v_pk_mul_f32 v[96:97], v[20:21], v[148:149]
	v_pk_mul_f32 v[114:115], v[22:23], v[134:135]
	v_pk_mul_f32 v[116:117], v[12:13], v[132:133]
	v_pk_mul_f32 v[118:119], v[14:15], v[130:131]
	v_pk_fma_f32 v[96:97], v[4:5], v[152:153], v[96:97]
	v_pk_fma_f32 v[114:115], v[6:7], v[150:151], v[114:115]
	v_pk_fma_f32 v[116:117], v[0:1], v[138:139], v[116:117]
	v_pk_fma_f32 v[118:119], v[2:3], v[136:137], v[118:119]
	v_pk_fma_f32 v[96:97], v[24:25], v[146:147], v[96:97]
	v_pk_fma_f32 v[114:115], v[26:27], v[128:129], v[114:115]
	v_pk_fma_f32 v[116:117], v[16:17], v[112:113], v[116:117]
	v_pk_fma_f32 v[118:119], v[18:19], v[110:111], v[118:119]
	v_lshlrev_b32_e32 v140, 16, v98
	v_and_b32_e32 v141, 0xffff0000, v98
	v_lshlrev_b32_e32 v98, 16, v99
	v_and_b32_e32 v99, 0xffff0000, v99
	v_pk_fma_f32 v[96:97], v[36:37], v[108:109], v[96:97]
	v_pk_fma_f32 v[114:115], v[38:39], v[106:107], v[114:115]
	v_pk_fma_f32 v[116:117], v[28:29], v[104:105], v[116:117]
	v_pk_fma_f32 v[118:119], v[30:31], v[102:103], v[118:119]
	v_pk_fma_f32 v[96:97], v[32:33], v[144:145], v[96:97]
	v_pk_fma_f32 v[114:115], v[34:35], v[142:143], v[114:115]
	v_pk_fma_f32 v[116:117], v[8:9], v[140:141], v[116:117]
	v_pk_fma_f32 v[118:119], v[10:11], v[98:99], v[118:119]
	v_mul_f32_e32 v126, 0xbfb8aa3b, v96
	v_mul_f32_e32 v127, 0xbfb8aa3b, v97
	v_mul_f32_e32 v136, 0xbfb8aa3b, v114
	v_mul_f32_e32 v137, 0xbfb8aa3b, v115
	v_mul_f32_e32 v138, 0xbfb8aa3b, v116
	v_mul_f32_e32 v139, 0xbfb8aa3b, v117
	v_mul_f32_e32 v150, 0xbfb8aa3b, v118
	v_mul_f32_e32 v151, 0xbfb8aa3b, v119
	v_exp_f32_e32 v126, v126
	v_exp_f32_e32 v127, v127
	v_exp_f32_e32 v136, v136
	v_exp_f32_e32 v137, v137
	v_exp_f32_e32 v138, v138
	v_exp_f32_e32 v139, v139
	v_exp_f32_e32 v150, v150
	v_exp_f32_e32 v151, v151
	v_add_f32_e32 v126, 1.0, v126
	v_add_f32_e32 v127, 1.0, v127
	v_add_f32_e32 v136, 1.0, v136
	v_add_f32_e32 v137, 1.0, v137
	v_add_f32_e32 v138, 1.0, v138
	v_add_f32_e32 v139, 1.0, v139
	v_add_f32_e32 v150, 1.0, v150
	v_add_f32_e32 v151, 1.0, v151
	v_rcp_f32_e32 v126, v126
	v_rcp_f32_e32 v127, v127
	v_rcp_f32_e32 v136, v136
	v_rcp_f32_e32 v137, v137
	v_rcp_f32_e32 v138, v138
	v_rcp_f32_e32 v139, v139
	v_rcp_f32_e32 v150, v150
	v_rcp_f32_e32 v151, v151
	v_pk_mul_f32 v[96:97], v[96:97], v[126:127]
	v_pk_mul_f32 v[114:115], v[114:115], v[136:137]
	v_pk_mul_f32 v[116:117], v[116:117], v[138:139]
	v_pk_mul_f32 v[118:119], v[118:119], v[150:151]
	s_and_saveexec_b64 s[24:25], vcc
	s_cbranch_execz .LBB0_315
	v_pk_mul_f32 v[126:127], v[96:97], v[96:97]
	v_pk_mul_f32 v[136:137], v[114:115], v[114:115]
	v_add_f32_e32 v126, v126, v127
	v_add_f32_e32 v126, v136, v126
	v_pk_mul_f32 v[138:139], v[116:117], v[116:117]
	v_add_f32_e32 v126, v137, v126
	v_and_b32_e32 v136, 64, v158
	v_add_f32_e32 v126, v138, v126
	v_xor_b32_e32 v127, 1, v158
	v_add_u32_e32 v136, 64, v136
	v_pk_mul_f32 v[150:151], v[118:119], v[118:119]
	v_add_f32_e32 v126, v139, v126
	v_cmp_lt_i32_e64 s[4:5], v127, v136
	v_add_f32_e32 v126, v150, v126
	v_add_f32_e32 v126, v151, v126
	v_cndmask_b32_e64 v127, v158, v127, s[4:5]
	v_lshlrev_b32_e32 v127, 2, v127
	s_nop 1
	v_mov_b32_dpp v127, v126 quad_perm:[1,0,3,2] row_mask:0xf bank_mask:0xf
	v_add_f32_e32 v126, v126, v127
	v_xor_b32_e32 v127, 2, v158
	v_cmp_lt_i32_e64 s[4:5], v127, v136
	s_nop 1
	v_cndmask_b32_e64 v127, v158, v127, s[4:5]
	v_lshlrev_b32_e32 v127, 2, v127
	s_nop 1
	v_mov_b32_dpp v127, v126 quad_perm:[2,3,0,1] row_mask:0xf bank_mask:0xf
	v_add_f32_e32 v126, v126, v127
	v_xor_b32_e32 v127, 4, v158
	v_cmp_lt_i32_e64 s[4:5], v127, v136
	s_nop 1
	v_cndmask_b32_e64 v127, v158, v127, s[4:5]
	v_lshlrev_b32_e32 v127, 2, v127
	s_nop 1
	v_mov_b32_dpp v127, v126 row_half_mirror row_mask:0xf bank_mask:0xf
	v_add_f32_e32 v126, v126, v127
	v_xor_b32_e32 v127, 8, v158
	v_cmp_lt_i32_e64 s[4:5], v127, v136
	s_nop 1
	v_cndmask_b32_e64 v127, v158, v127, s[4:5]
	v_lshlrev_b32_e32 v127, 2, v127
	s_nop 1
	v_mov_b32_dpp v127, v126 row_ror:8 row_mask:0xf bank_mask:0xf
	v_add_f32_e32 v126, v126, v127
	v_add_f32_e32 v126, 0x358637bd, v126
	v_mul_f32_e32 v127, 0x4b800000, v126
	v_cmp_gt_f32_e64 s[4:5], s46, v126
	s_nop 1
	v_cndmask_b32_e64 v126, v126, v127, s[4:5]
	v_rsq_f32_e32 v126, v126
	s_nop 0
	v_mul_f32_e32 v127, 0x45800000, v126
	v_cndmask_b32_e64 v126, v126, v127, s[4:5]
	v_mul_f32_e32 v126, v157, v126
	v_pk_mul_f32 v[118:119], v[118:119], v[126:127] op_sel_hi:[1,0]
	v_pk_mul_f32 v[116:117], v[116:117], v[126:127] op_sel_hi:[1,0]
	v_pk_mul_f32 v[114:115], v[114:115], v[126:127] op_sel_hi:[1,0]
	v_pk_mul_f32 v[96:97], v[96:97], v[126:127] op_sel_hi:[1,0]
; DI unsigned pk2(float a, float b) { f32x2 v = {a, b}; bf16x2_t r = __builtin_convertvector(v, bf16x2_t); return __builtin_bit_cast(unsigned, r); }
; DI float bflo(unsigned u) { return __uint_as_float(u << 16); }
; DI float bfhi(unsigned u) { return __uint_as_float(u & 0xffff0000u); }
; DI float siluf_(float x) { return x * __builtin_amdgcn_rcpf(1.f + __expf(-x)); }
; DI void dn_conv_phase(const Params& p) {
;     ...
;         for (int tt = 0; tt < SEG; ++tt) {
;             { const u32x4 u = rows[tt + 4]; const int sl = (tt + 4) % 5;
;               ring[sl][0] = (f32x2){bflo(u.x), bfhi(u.x)}; ring[sl][1] = (f32x2){bflo(u.y), bfhi(u.y)}; ring[sl][2] = (f32x2){bflo(u.z), bfhi(u.z)}; ring[sl][3] = (f32x2){bflo(u.w), bfhi(u.w)}; }
;             f32x2 o2[4];
; #pragma unroll
;             for (int e = 0; e < 4; ++e) o2[e] = w[0][e] * ring[tt % 5][e];
; #pragma unroll
;             for (int j = 1; j < 5; ++j)
; #pragma unroll
;                 for (int e = 0; e < 4; ++e) o2[e] += w[j][e] * ring[(tt + j) % 5][e];
;             float o[8];
; #pragma unroll
;             for (int e = 0; e < 4; ++e) { o[2 * e] = siluf_(o2[e].x); o[2 * e + 1] = siluf_(o2[e].y); }
;             if (part < 2) {
;                 float ss = 0.f;
; #pragma unroll
;                 for (int e = 0; e < 8; ++e) ss += o[e] * o[e];
;                 ss += __shfl_xor(ss, 1); ss += __shfl_xor(ss, 2); ss += __shfl_xor(ss, 4); ss += __shfl_xor(ss, 8);
;                 const float sc = rsqrtf(ss + EPS) * (part == 0 ? 0.08838834764831845f : 1.f);
; #pragma unroll
;                 for (int e = 0; e < 8; ++e) o[e] *= sc;
;             }
;             u32x4 ov; ov.x = pk2(o[0], o[1]); ov.y = pk2(o[2], o[3]); ov.z = pk2(o[4], o[5]); ov.w = pk2(o[6], o[7]);
;             *(u32x4*)(QKV + (size_t)(row0 + tt) * 1536 + ch) = ov;
.LBB0_315:
	s_or_b64 exec, exec, s[24:25]
	v_cvt_pk_bf16_f32 v136, v96, v97
	v_or_b32_e32 v96, 1, v156
	v_cvt_pk_bf16_f32 v137, v114, v115
	v_cvt_pk_bf16_f32 v138, v116, v117
	v_cvt_pk_bf16_f32 v139, v118, v119
	v_mad_i64_i32 v[96:97], s[4:5], v96, s45, v[100:101]
	global_store_dwordx4 v[96:97], v[136:139], off
	v_lshlrev_b32_e32 v96, 16, v94
	v_and_b32_e32 v97, 0xffff0000, v94
	v_lshlrev_b32_e32 v138, 16, v92
	v_and_b32_e32 v139, 0xffff0000, v92
	v_lshlrev_b32_e32 v136, 16, v93
	v_and_b32_e32 v137, 0xffff0000, v93
	v_lshlrev_b32_e32 v92, 16, v95
	v_and_b32_e32 v93, 0xffff0000, v95
	v_pk_mul_f32 v[94:95], v[20:21], v[146:147]
	v_pk_mul_f32 v[114:115], v[22:23], v[128:129]
	v_pk_mul_f32 v[116:117], v[12:13], v[112:113]
	v_pk_mul_f32 v[118:119], v[14:15], v[110:111]
	v_pk_fma_f32 v[94:95], v[4:5], v[148:149], v[94:95]
	v_pk_fma_f32 v[114:115], v[6:7], v[134:135], v[114:115]
	v_pk_fma_f32 v[116:117], v[0:1], v[132:133], v[116:117]
	v_pk_fma_f32 v[118:119], v[2:3], v[130:131], v[118:119]
	v_pk_fma_f32 v[94:95], v[24:25], v[108:109], v[94:95]
	v_pk_fma_f32 v[114:115], v[26:27], v[106:107], v[114:115]
	v_pk_fma_f32 v[116:117], v[16:17], v[104:105], v[116:117]
	v_pk_fma_f32 v[118:119], v[18:19], v[102:103], v[118:119]
	v_pk_fma_f32 v[94:95], v[36:37], v[144:145], v[94:95]
	v_pk_fma_f32 v[114:115], v[38:39], v[142:143], v[114:115]
	v_pk_fma_f32 v[116:117], v[28:29], v[140:141], v[116:117]
	v_pk_fma_f32 v[118:119], v[30:31], v[98:99], v[118:119]
	v_pk_fma_f32 v[94:95], v[32:33], v[138:139], v[94:95]
	v_pk_fma_f32 v[114:115], v[34:35], v[136:137], v[114:115]
	v_pk_fma_f32 v[116:117], v[8:9], v[96:97], v[116:117]
	v_pk_fma_f32 v[118:119], v[10:11], v[92:93], v[118:119]
	v_mul_f32_e32 v126, 0xbfb8aa3b, v94
	v_mul_f32_e32 v127, 0xbfb8aa3b, v95
	v_mul_f32_e32 v130, 0xbfb8aa3b, v114
	v_mul_f32_e32 v131, 0xbfb8aa3b, v115
	v_mul_f32_e32 v132, 0xbfb8aa3b, v116
	v_mul_f32_e32 v133, 0xbfb8aa3b, v117
	v_mul_f32_e32 v134, 0xbfb8aa3b, v118
	v_mul_f32_e32 v135, 0xbfb8aa3b, v119
	v_exp_f32_e32 v126, v126
	v_exp_f32_e32 v127, v127
	v_exp_f32_e32 v130, v130
	v_exp_f32_e32 v131, v131
	v_exp_f32_e32 v132, v132
	v_exp_f32_e32 v133, v133
	v_exp_f32_e32 v134, v134
	v_exp_f32_e32 v135, v135
	v_add_f32_e32 v126, 1.0, v126
	v_add_f32_e32 v127, 1.0, v127
	v_add_f32_e32 v130, 1.0, v130
	v_add_f32_e32 v131, 1.0, v131
	v_add_f32_e32 v132, 1.0, v132
	v_add_f32_e32 v133, 1.0, v133
	v_add_f32_e32 v134, 1.0, v134
	v_add_f32_e32 v135, 1.0, v135
	v_rcp_f32_e32 v126, v126
	v_rcp_f32_e32 v127, v127
	v_rcp_f32_e32 v130, v130
	v_rcp_f32_e32 v131, v131
	v_rcp_f32_e32 v132, v132
	v_rcp_f32_e32 v133, v133
	v_rcp_f32_e32 v134, v134
	v_rcp_f32_e32 v135, v135
	v_pk_mul_f32 v[94:95], v[94:95], v[126:127]
	v_pk_mul_f32 v[114:115], v[114:115], v[130:131]
	v_pk_mul_f32 v[116:117], v[116:117], v[132:133]
	v_pk_mul_f32 v[118:119], v[118:119], v[134:135]
	s_and_saveexec_b64 s[24:25], vcc
	s_cbranch_execz .LBB0_317
	v_pk_mul_f32 v[126:127], v[94:95], v[94:95]
	v_pk_mul_f32 v[130:131], v[114:115], v[114:115]
	v_add_f32_e32 v126, v126, v127
	v_add_f32_e32 v126, v130, v126
	v_pk_mul_f32 v[132:133], v[116:117], v[116:117]
	v_add_f32_e32 v126, v131, v126
	v_and_b32_e32 v130, 64, v158
	v_add_f32_e32 v126, v132, v126
	v_xor_b32_e32 v127, 1, v158
	v_add_u32_e32 v130, 64, v130
	v_pk_mul_f32 v[134:135], v[118:119], v[118:119]
	v_add_f32_e32 v126, v133, v126
	v_cmp_lt_i32_e64 s[4:5], v127, v130
	v_add_f32_e32 v126, v134, v126
	v_add_f32_e32 v126, v135, v126
	v_cndmask_b32_e64 v127, v158, v127, s[4:5]
	v_lshlrev_b32_e32 v127, 2, v127
	s_nop 1
	v_mov_b32_dpp v127, v126 quad_perm:[1,0,3,2] row_mask:0xf bank_mask:0xf
	v_add_f32_e32 v126, v126, v127
	v_xor_b32_e32 v127, 2, v158
	v_cmp_lt_i32_e64 s[4:5], v127, v130
	s_nop 1
	v_cndmask_b32_e64 v127, v158, v127, s[4:5]
	v_lshlrev_b32_e32 v127, 2, v127
	s_nop 1
	v_mov_b32_dpp v127, v126 quad_perm:[2,3,0,1] row_mask:0xf bank_mask:0xf
	v_add_f32_e32 v126, v126, v127
	v_xor_b32_e32 v127, 4, v158
	v_cmp_lt_i32_e64 s[4:5], v127, v130
	s_nop 1
	v_cndmask_b32_e64 v127, v158, v127, s[4:5]
	v_lshlrev_b32_e32 v127, 2, v127
	s_nop 1
	v_mov_b32_dpp v127, v126 row_half_mirror row_mask:0xf bank_mask:0xf
	v_add_f32_e32 v126, v126, v127
	v_xor_b32_e32 v127, 8, v158
	v_cmp_lt_i32_e64 s[4:5], v127, v130
	s_nop 1
	v_cndmask_b32_e64 v127, v158, v127, s[4:5]
	v_lshlrev_b32_e32 v127, 2, v127
	s_nop 1
	v_mov_b32_dpp v127, v126 row_ror:8 row_mask:0xf bank_mask:0xf
	v_add_f32_e32 v126, v126, v127
	v_add_f32_e32 v126, 0x358637bd, v126
	v_mul_f32_e32 v127, 0x4b800000, v126
	v_cmp_gt_f32_e64 s[4:5], s46, v126
	s_nop 1
	v_cndmask_b32_e64 v126, v126, v127, s[4:5]
	v_rsq_f32_e32 v126, v126
	s_nop 0
	v_mul_f32_e32 v127, 0x45800000, v126
	v_cndmask_b32_e64 v126, v126, v127, s[4:5]
	v_mul_f32_e32 v126, v157, v126
	v_pk_mul_f32 v[118:119], v[118:119], v[126:127] op_sel_hi:[1,0]
	v_pk_mul_f32 v[116:117], v[116:117], v[126:127] op_sel_hi:[1,0]
	v_pk_mul_f32 v[114:115], v[114:115], v[126:127] op_sel_hi:[1,0]
	v_pk_mul_f32 v[94:95], v[94:95], v[126:127] op_sel_hi:[1,0]
; DI unsigned pk2(float a, float b) { f32x2 v = {a, b}; bf16x2_t r = __builtin_convertvector(v, bf16x2_t); return __builtin_bit_cast(unsigned, r); }
; DI float bflo(unsigned u) { return __uint_as_float(u << 16); }
; DI float bfhi(unsigned u) { return __uint_as_float(u & 0xffff0000u); }
; DI float siluf_(float x) { return x * __builtin_amdgcn_rcpf(1.f + __expf(-x)); }
; DI void dn_conv_phase(const Params& p) {
;     ...
;         for (int tt = 0; tt < SEG; ++tt) {
;             { const u32x4 u = rows[tt + 4]; const int sl = (tt + 4) % 5;
;               ring[sl][0] = (f32x2){bflo(u.x), bfhi(u.x)}; ring[sl][1] = (f32x2){bflo(u.y), bfhi(u.y)}; ring[sl][2] = (f32x2){bflo(u.z), bfhi(u.z)}; ring[sl][3] = (f32x2){bflo(u.w), bfhi(u.w)}; }
;             f32x2 o2[4];
; #pragma unroll
;             for (int e = 0; e < 4; ++e) o2[e] = w[0][e] * ring[tt % 5][e];
; #pragma unroll
;             for (int j = 1; j < 5; ++j)
; #pragma unroll
;                 for (int e = 0; e < 4; ++e) o2[e] += w[j][e] * ring[(tt + j) % 5][e];
;             float o[8];
; #pragma unroll
;             for (int e = 0; e < 4; ++e) { o[2 * e] = siluf_(o2[e].x); o[2 * e + 1] = siluf_(o2[e].y); }
;             if (part < 2) {
;                 float ss = 0.f;
; #pragma unroll
;                 for (int e = 0; e < 8; ++e) ss += o[e] * o[e];
;                 ss += __shfl_xor(ss, 1); ss += __shfl_xor(ss, 2); ss += __shfl_xor(ss, 4); ss += __shfl_xor(ss, 8);
;                 const float sc = rsqrtf(ss + EPS) * (part == 0 ? 0.08838834764831845f : 1.f);
; #pragma unroll
;                 for (int e = 0; e < 8; ++e) o[e] *= sc;
;             }
;             u32x4 ov; ov.x = pk2(o[0], o[1]); ov.y = pk2(o[2], o[3]); ov.z = pk2(o[4], o[5]); ov.w = pk2(o[6], o[7]);
;             *(u32x4*)(QKV + (size_t)(row0 + tt) * 1536 + ch) = ov;
.LBB0_317:
	s_or_b64 exec, exec, s[24:25]
	v_cvt_pk_bf16_f32 v130, v94, v95
	v_or_b32_e32 v94, 2, v156
	v_cvt_pk_bf16_f32 v131, v114, v115
	v_cvt_pk_bf16_f32 v132, v116, v117
	v_cvt_pk_bf16_f32 v133, v118, v119
	v_mad_i64_i32 v[94:95], s[4:5], v94, s45, v[100:101]
	global_store_dwordx4 v[94:95], v[130:133], off
	v_lshlrev_b32_e32 v134, 16, v88
	v_and_b32_e32 v135, 0xffff0000, v88
	v_lshlrev_b32_e32 v132, 16, v89
	v_and_b32_e32 v133, 0xffff0000, v89
	v_lshlrev_b32_e32 v130, 16, v90
	v_and_b32_e32 v131, 0xffff0000, v90
	v_lshlrev_b32_e32 v88, 16, v91
	v_and_b32_e32 v89, 0xffff0000, v91
	v_pk_mul_f32 v[90:91], v[20:21], v[108:109]
	v_pk_mul_f32 v[114:115], v[12:13], v[104:105]
	v_pk_fma_f32 v[90:91], v[4:5], v[146:147], v[90:91]
	v_pk_fma_f32 v[112:113], v[0:1], v[112:113], v[114:115]
	v_pk_fma_f32 v[90:91], v[24:25], v[144:145], v[90:91]
	v_pk_mul_f32 v[114:115], v[14:15], v[102:103]
	v_pk_fma_f32 v[90:91], v[36:37], v[138:139], v[90:91]
	v_pk_fma_f32 v[110:111], v[2:3], v[110:111], v[114:115]
	v_pk_fma_f32 v[90:91], v[32:33], v[134:135], v[90:91]
	v_pk_mul_f32 v[94:95], v[22:23], v[106:107]
	v_mul_f32_e32 v114, 0xbfb8aa3b, v90
	v_exp_f32_e32 v116, v114
	v_mul_f32_e32 v114, 0xbfb8aa3b, v91
	v_pk_fma_f32 v[94:95], v[6:7], v[128:129], v[94:95]
	v_exp_f32_e32 v117, v114
	v_pk_fma_f32 v[94:95], v[26:27], v[142:143], v[94:95]
	v_pk_fma_f32 v[112:113], v[16:17], v[140:141], v[112:113]
	v_pk_fma_f32 v[110:111], v[18:19], v[98:99], v[110:111]
	v_pk_fma_f32 v[94:95], v[38:39], v[136:137], v[94:95]
	v_pk_fma_f32 v[112:113], v[28:29], v[96:97], v[112:113]
	v_pk_fma_f32 v[110:111], v[30:31], v[92:93], v[110:111]
	v_pk_fma_f32 v[94:95], v[34:35], v[132:133], v[94:95]
	v_pk_fma_f32 v[112:113], v[8:9], v[130:131], v[112:113]
	v_pk_fma_f32 v[114:115], v[10:11], v[88:89], v[110:111]
	v_add_f32_e32 v110, 1.0, v116
	v_add_f32_e32 v111, 1.0, v117
	v_mul_f32_e32 v116, 0xbfb8aa3b, v94
	v_mul_f32_e32 v117, 0xbfb8aa3b, v95
	v_mul_f32_e32 v118, 0xbfb8aa3b, v112
	v_mul_f32_e32 v119, 0xbfb8aa3b, v113
	v_mul_f32_e32 v126, 0xbfb8aa3b, v114
	v_mul_f32_e32 v127, 0xbfb8aa3b, v115
	v_exp_f32_e32 v116, v116
	v_exp_f32_e32 v117, v117
	v_exp_f32_e32 v118, v118
	v_exp_f32_e32 v119, v119
	v_exp_f32_e32 v126, v126
	v_exp_f32_e32 v127, v127
	v_add_f32_e32 v116, 1.0, v116
	v_add_f32_e32 v117, 1.0, v117
	v_add_f32_e32 v118, 1.0, v118
	v_add_f32_e32 v119, 1.0, v119
	v_add_f32_e32 v126, 1.0, v126
	v_add_f32_e32 v127, 1.0, v127
	v_rcp_f32_e32 v110, v110
	v_rcp_f32_e32 v111, v111
	v_rcp_f32_e32 v116, v116
	v_rcp_f32_e32 v117, v117
	v_rcp_f32_e32 v118, v118
	v_rcp_f32_e32 v119, v119
	v_rcp_f32_e32 v126, v126
	v_rcp_f32_e32 v127, v127
	v_pk_mul_f32 v[90:91], v[90:91], v[110:111]
	v_pk_mul_f32 v[94:95], v[94:95], v[116:117]
	v_pk_mul_f32 v[110:111], v[112:113], v[118:119]
	v_pk_mul_f32 v[112:113], v[114:115], v[126:127]
	s_and_saveexec_b64 s[24:25], vcc
	s_cbranch_execz .LBB0_319
	v_pk_mul_f32 v[114:115], v[90:91], v[90:91]
	v_pk_mul_f32 v[116:117], v[94:95], v[94:95]
	v_add_f32_e32 v114, v114, v115
	v_add_f32_e32 v114, v116, v114
	v_pk_mul_f32 v[118:119], v[110:111], v[110:111]
	v_add_f32_e32 v114, v117, v114
	v_and_b32_e32 v116, 64, v158
	v_add_f32_e32 v114, v118, v114
	v_xor_b32_e32 v115, 1, v158
	v_add_u32_e32 v116, 64, v116
	v_pk_mul_f32 v[126:127], v[112:113], v[112:113]
	v_add_f32_e32 v114, v119, v114
	v_cmp_lt_i32_e64 s[4:5], v115, v116
	v_add_f32_e32 v114, v126, v114
	v_add_f32_e32 v114, v127, v114
	v_cndmask_b32_e64 v115, v158, v115, s[4:5]
	v_lshlrev_b32_e32 v115, 2, v115
	s_nop 1
	v_mov_b32_dpp v115, v114 quad_perm:[1,0,3,2] row_mask:0xf bank_mask:0xf
	v_add_f32_e32 v114, v114, v115
	v_xor_b32_e32 v115, 2, v158
	v_cmp_lt_i32_e64 s[4:5], v115, v116
	s_nop 1
	v_cndmask_b32_e64 v115, v158, v115, s[4:5]
	v_lshlrev_b32_e32 v115, 2, v115
	s_nop 1
	v_mov_b32_dpp v115, v114 quad_perm:[2,3,0,1] row_mask:0xf bank_mask:0xf
	v_add_f32_e32 v114, v114, v115
	v_xor_b32_e32 v115, 4, v158
	v_cmp_lt_i32_e64 s[4:5], v115, v116
	s_nop 1
	v_cndmask_b32_e64 v115, v158, v115, s[4:5]
	v_lshlrev_b32_e32 v115, 2, v115
	s_nop 1
	v_mov_b32_dpp v115, v114 row_half_mirror row_mask:0xf bank_mask:0xf
	v_add_f32_e32 v114, v114, v115
	v_xor_b32_e32 v115, 8, v158
	v_cmp_lt_i32_e64 s[4:5], v115, v116
	s_nop 1
	v_cndmask_b32_e64 v115, v158, v115, s[4:5]
	v_lshlrev_b32_e32 v115, 2, v115
	s_nop 1
	v_mov_b32_dpp v115, v114 row_ror:8 row_mask:0xf bank_mask:0xf
	v_add_f32_e32 v114, v114, v115
	v_add_f32_e32 v114, 0x358637bd, v114
	v_mul_f32_e32 v115, 0x4b800000, v114
	v_cmp_gt_f32_e64 s[4:5], s46, v114
	s_nop 1
	v_cndmask_b32_e64 v114, v114, v115, s[4:5]
	v_rsq_f32_e32 v114, v114
	s_nop 0
	v_mul_f32_e32 v115, 0x45800000, v114
	v_cndmask_b32_e64 v114, v114, v115, s[4:5]
	v_mul_f32_e32 v114, v157, v114
	v_pk_mul_f32 v[112:113], v[112:113], v[114:115] op_sel_hi:[1,0]
	v_pk_mul_f32 v[110:111], v[110:111], v[114:115] op_sel_hi:[1,0]
	v_pk_mul_f32 v[94:95], v[94:95], v[114:115] op_sel_hi:[1,0]
	v_pk_mul_f32 v[90:91], v[90:91], v[114:115] op_sel_hi:[1,0]
; DI unsigned pk2(float a, float b) { f32x2 v = {a, b}; bf16x2_t r = __builtin_convertvector(v, bf16x2_t); return __builtin_bit_cast(unsigned, r); }
; DI float bflo(unsigned u) { return __uint_as_float(u << 16); }
; DI float bfhi(unsigned u) { return __uint_as_float(u & 0xffff0000u); }
; DI float siluf_(float x) { return x * __builtin_amdgcn_rcpf(1.f + __expf(-x)); }
; DI void dn_conv_phase(const Params& p) {
;     ...
;         for (int tt = 0; tt < SEG; ++tt) {
;             { const u32x4 u = rows[tt + 4]; const int sl = (tt + 4) % 5;
;               ring[sl][0] = (f32x2){bflo(u.x), bfhi(u.x)}; ring[sl][1] = (f32x2){bflo(u.y), bfhi(u.y)}; ring[sl][2] = (f32x2){bflo(u.z), bfhi(u.z)}; ring[sl][3] = (f32x2){bflo(u.w), bfhi(u.w)}; }
;             f32x2 o2[4];
; #pragma unroll
;             for (int e = 0; e < 4; ++e) o2[e] = w[0][e] * ring[tt % 5][e];
; #pragma unroll
;             for (int j = 1; j < 5; ++j)
; #pragma unroll
;                 for (int e = 0; e < 4; ++e) o2[e] += w[j][e] * ring[(tt + j) % 5][e];
;             float o[8];
; #pragma unroll
;             for (int e = 0; e < 4; ++e) { o[2 * e] = siluf_(o2[e].x); o[2 * e + 1] = siluf_(o2[e].y); }
;             if (part < 2) {
;                 float ss = 0.f;
; #pragma unroll
;                 for (int e = 0; e < 8; ++e) ss += o[e] * o[e];
;                 ss += __shfl_xor(ss, 1); ss += __shfl_xor(ss, 2); ss += __shfl_xor(ss, 4); ss += __shfl_xor(ss, 8);
;                 const float sc = rsqrtf(ss + EPS) * (part == 0 ? 0.08838834764831845f : 1.f);
; #pragma unroll
;                 for (int e = 0; e < 8; ++e) o[e] *= sc;
;             }
;             u32x4 ov; ov.x = pk2(o[0], o[1]); ov.y = pk2(o[2], o[3]); ov.z = pk2(o[4], o[5]); ov.w = pk2(o[6], o[7]);
;             *(u32x4*)(QKV + (size_t)(row0 + tt) * 1536 + ch) = ov;
.LBB0_319:
	s_or_b64 exec, exec, s[24:25]
	v_cvt_pk_bf16_f32 v114, v90, v91
	v_or_b32_e32 v90, 3, v156
	v_cvt_pk_bf16_f32 v115, v94, v95
	v_cvt_pk_bf16_f32 v116, v110, v111
	v_cvt_pk_bf16_f32 v117, v112, v113
	v_mad_i64_i32 v[90:91], s[4:5], v90, s45, v[100:101]
	global_store_dwordx4 v[90:91], v[114:117], off
	v_lshlrev_b32_e32 v128, 16, v84
	v_and_b32_e32 v129, 0xffff0000, v84
	v_lshlrev_b32_e32 v126, 16, v85
	v_and_b32_e32 v127, 0xffff0000, v85
	v_lshlrev_b32_e32 v118, 16, v86
	v_and_b32_e32 v119, 0xffff0000, v86
	v_lshlrev_b32_e32 v116, 16, v87
	v_and_b32_e32 v117, 0xffff0000, v87
	v_pk_mul_f32 v[84:85], v[20:21], v[144:145]
	v_pk_mul_f32 v[86:87], v[22:23], v[142:143]
	v_pk_mul_f32 v[90:91], v[12:13], v[140:141]
	v_pk_mul_f32 v[94:95], v[14:15], v[98:99]
	v_pk_fma_f32 v[84:85], v[4:5], v[108:109], v[84:85]
	v_pk_fma_f32 v[86:87], v[6:7], v[106:107], v[86:87]
	v_pk_fma_f32 v[90:91], v[0:1], v[104:105], v[90:91]
	v_pk_fma_f32 v[94:95], v[2:3], v[102:103], v[94:95]
	v_pk_fma_f32 v[84:85], v[24:25], v[138:139], v[84:85]
	v_pk_fma_f32 v[86:87], v[26:27], v[136:137], v[86:87]
	v_pk_fma_f32 v[90:91], v[16:17], v[96:97], v[90:91]
	v_pk_fma_f32 v[94:95], v[18:19], v[92:93], v[94:95]
	v_pk_fma_f32 v[84:85], v[36:37], v[134:135], v[84:85]
	v_pk_fma_f32 v[86:87], v[38:39], v[132:133], v[86:87]
	v_pk_fma_f32 v[90:91], v[28:29], v[130:131], v[90:91]
	v_pk_fma_f32 v[94:95], v[30:31], v[88:89], v[94:95]
	v_pk_fma_f32 v[84:85], v[32:33], v[128:129], v[84:85]
	v_pk_fma_f32 v[86:87], v[34:35], v[126:127], v[86:87]
	v_pk_fma_f32 v[90:91], v[8:9], v[118:119], v[90:91]
	v_pk_fma_f32 v[94:95], v[10:11], v[116:117], v[94:95]
	v_mul_f32_e32 v102, 0xbfb8aa3b, v84
	v_mul_f32_e32 v103, 0xbfb8aa3b, v85
	v_mul_f32_e32 v104, 0xbfb8aa3b, v86
	v_mul_f32_e32 v105, 0xbfb8aa3b, v87
	v_mul_f32_e32 v106, 0xbfb8aa3b, v90
	v_mul_f32_e32 v107, 0xbfb8aa3b, v91
	v_mul_f32_e32 v108, 0xbfb8aa3b, v94
	v_mul_f32_e32 v109, 0xbfb8aa3b, v95
	v_exp_f32_e32 v102, v102
	v_exp_f32_e32 v103, v103
	v_exp_f32_e32 v104, v104
	v_exp_f32_e32 v105, v105
	v_exp_f32_e32 v106, v106
	v_exp_f32_e32 v107, v107
	v_exp_f32_e32 v108, v108
	v_exp_f32_e32 v109, v109
	v_add_f32_e32 v102, 1.0, v102
	v_add_f32_e32 v103, 1.0, v103
	v_add_f32_e32 v104, 1.0, v104
	v_add_f32_e32 v105, 1.0, v105
	v_add_f32_e32 v106, 1.0, v106
	v_add_f32_e32 v107, 1.0, v107
	v_add_f32_e32 v108, 1.0, v108
	v_add_f32_e32 v109, 1.0, v109
	v_rcp_f32_e32 v102, v102
	v_rcp_f32_e32 v103, v103
	v_rcp_f32_e32 v104, v104
	v_rcp_f32_e32 v105, v105
	v_rcp_f32_e32 v106, v106
	v_rcp_f32_e32 v107, v107
	v_rcp_f32_e32 v108, v108
	v_rcp_f32_e32 v109, v109
	v_pk_mul_f32 v[84:85], v[84:85], v[102:103]
	v_pk_mul_f32 v[86:87], v[86:87], v[104:105]
	v_pk_mul_f32 v[90:91], v[90:91], v[106:107]
	v_pk_mul_f32 v[94:95], v[94:95], v[108:109]
	s_and_saveexec_b64 s[24:25], vcc
	s_cbranch_execz .LBB0_321
	v_pk_mul_f32 v[102:103], v[84:85], v[84:85]
	v_pk_mul_f32 v[104:105], v[86:87], v[86:87]
	v_add_f32_e32 v102, v102, v103
	v_add_f32_e32 v102, v104, v102
	v_pk_mul_f32 v[106:107], v[90:91], v[90:91]
	v_add_f32_e32 v102, v105, v102
	v_and_b32_e32 v104, 64, v158
	v_add_f32_e32 v102, v106, v102
	v_xor_b32_e32 v103, 1, v158
	v_add_u32_e32 v104, 64, v104
	v_pk_mul_f32 v[108:109], v[94:95], v[94:95]
	v_add_f32_e32 v102, v107, v102
	v_cmp_lt_i32_e64 s[4:5], v103, v104
	v_add_f32_e32 v102, v108, v102
	v_add_f32_e32 v102, v109, v102
	v_cndmask_b32_e64 v103, v158, v103, s[4:5]
	v_lshlrev_b32_e32 v103, 2, v103
	s_nop 1
	v_mov_b32_dpp v103, v102 quad_perm:[1,0,3,2] row_mask:0xf bank_mask:0xf
	v_add_f32_e32 v102, v102, v103
	v_xor_b32_e32 v103, 2, v158
	v_cmp_lt_i32_e64 s[4:5], v103, v104
	s_nop 1
	v_cndmask_b32_e64 v103, v158, v103, s[4:5]
	v_lshlrev_b32_e32 v103, 2, v103
	s_nop 1
	v_mov_b32_dpp v103, v102 quad_perm:[2,3,0,1] row_mask:0xf bank_mask:0xf
	v_add_f32_e32 v102, v102, v103
	v_xor_b32_e32 v103, 4, v158
	v_cmp_lt_i32_e64 s[4:5], v103, v104
	s_nop 1
	v_cndmask_b32_e64 v103, v158, v103, s[4:5]
	v_lshlrev_b32_e32 v103, 2, v103
	s_nop 1
	v_mov_b32_dpp v103, v102 row_half_mirror row_mask:0xf bank_mask:0xf
	v_add_f32_e32 v102, v102, v103
	v_xor_b32_e32 v103, 8, v158
	v_cmp_lt_i32_e64 s[4:5], v103, v104
	s_nop 1
	v_cndmask_b32_e64 v103, v158, v103, s[4:5]
	v_lshlrev_b32_e32 v103, 2, v103
	s_nop 1
	v_mov_b32_dpp v103, v102 row_ror:8 row_mask:0xf bank_mask:0xf
	v_add_f32_e32 v102, v102, v103
	v_add_f32_e32 v102, 0x358637bd, v102
	v_mul_f32_e32 v103, 0x4b800000, v102
	v_cmp_gt_f32_e64 s[4:5], s46, v102
	s_nop 1
	v_cndmask_b32_e64 v102, v102, v103, s[4:5]
	v_rsq_f32_e32 v102, v102
	s_nop 0
	v_mul_f32_e32 v103, 0x45800000, v102
	v_cndmask_b32_e64 v102, v102, v103, s[4:5]
	v_mul_f32_e32 v102, v157, v102
	v_pk_mul_f32 v[94:95], v[94:95], v[102:103] op_sel_hi:[1,0]
	v_pk_mul_f32 v[90:91], v[90:91], v[102:103] op_sel_hi:[1,0]
	v_pk_mul_f32 v[86:87], v[86:87], v[102:103] op_sel_hi:[1,0]
	v_pk_mul_f32 v[84:85], v[84:85], v[102:103] op_sel_hi:[1,0]
; DI unsigned pk2(float a, float b) { f32x2 v = {a, b}; bf16x2_t r = __builtin_convertvector(v, bf16x2_t); return __builtin_bit_cast(unsigned, r); }
; DI float bflo(unsigned u) { return __uint_as_float(u << 16); }
; DI float bfhi(unsigned u) { return __uint_as_float(u & 0xffff0000u); }
; DI float siluf_(float x) { return x * __builtin_amdgcn_rcpf(1.f + __expf(-x)); }
; DI void dn_conv_phase(const Params& p) {
;     ...
;         for (int tt = 0; tt < SEG; ++tt) {
;             { const u32x4 u = rows[tt + 4]; const int sl = (tt + 4) % 5;
;               ring[sl][0] = (f32x2){bflo(u.x), bfhi(u.x)}; ring[sl][1] = (f32x2){bflo(u.y), bfhi(u.y)}; ring[sl][2] = (f32x2){bflo(u.z), bfhi(u.z)}; ring[sl][3] = (f32x2){bflo(u.w), bfhi(u.w)}; }
;             f32x2 o2[4];
; #pragma unroll
;             for (int e = 0; e < 4; ++e) o2[e] = w[0][e] * ring[tt % 5][e];
; #pragma unroll
;             for (int j = 1; j < 5; ++j)
; #pragma unroll
;                 for (int e = 0; e < 4; ++e) o2[e] += w[j][e] * ring[(tt + j) % 5][e];
;             float o[8];
; #pragma unroll
;             for (int e = 0; e < 4; ++e) { o[2 * e] = siluf_(o2[e].x); o[2 * e + 1] = siluf_(o2[e].y); }
;             if (part < 2) {
;                 float ss = 0.f;
; #pragma unroll
;                 for (int e = 0; e < 8; ++e) ss += o[e] * o[e];
;                 ss += __shfl_xor(ss, 1); ss += __shfl_xor(ss, 2); ss += __shfl_xor(ss, 4); ss += __shfl_xor(ss, 8);
;                 const float sc = rsqrtf(ss + EPS) * (part == 0 ? 0.08838834764831845f : 1.f);
; #pragma unroll
;                 for (int e = 0; e < 8; ++e) o[e] *= sc;
;             }
;             u32x4 ov; ov.x = pk2(o[0], o[1]); ov.y = pk2(o[2], o[3]); ov.z = pk2(o[4], o[5]); ov.w = pk2(o[6], o[7]);
;             *(u32x4*)(QKV + (size_t)(row0 + tt) * 1536 + ch) = ov;
.LBB0_321:
	s_or_b64 exec, exec, s[24:25]
	v_cvt_pk_bf16_f32 v84, v84, v85
	v_cvt_pk_bf16_f32 v85, v86, v87
	v_cvt_pk_bf16_f32 v86, v90, v91
	v_or_b32_e32 v90, 4, v156
	v_cvt_pk_bf16_f32 v87, v94, v95
	v_mad_i64_i32 v[90:91], s[4:5], v90, s45, v[100:101]
	global_store_dwordx4 v[90:91], v[84:87], off
	v_lshlrev_b32_e32 v114, 16, v80
	v_and_b32_e32 v115, 0xffff0000, v80
	v_lshlrev_b32_e32 v112, 16, v81
	v_and_b32_e32 v113, 0xffff0000, v81
	v_lshlrev_b32_e32 v110, 16, v82
	v_and_b32_e32 v111, 0xffff0000, v82
	v_lshlrev_b32_e32 v108, 16, v83
	v_and_b32_e32 v109, 0xffff0000, v83
	v_pk_mul_f32 v[80:81], v[20:21], v[138:139]
	v_pk_mul_f32 v[82:83], v[22:23], v[136:137]
	v_pk_mul_f32 v[84:85], v[12:13], v[96:97]
	v_pk_mul_f32 v[86:87], v[14:15], v[92:93]
	v_pk_fma_f32 v[80:81], v[4:5], v[144:145], v[80:81]
	v_pk_fma_f32 v[82:83], v[6:7], v[142:143], v[82:83]
	v_pk_fma_f32 v[84:85], v[0:1], v[140:141], v[84:85]
	v_pk_fma_f32 v[86:87], v[2:3], v[98:99], v[86:87]
	v_pk_fma_f32 v[80:81], v[24:25], v[134:135], v[80:81]
	v_pk_fma_f32 v[82:83], v[26:27], v[132:133], v[82:83]
	v_pk_fma_f32 v[84:85], v[16:17], v[130:131], v[84:85]
	v_pk_fma_f32 v[86:87], v[18:19], v[88:89], v[86:87]
	v_pk_fma_f32 v[80:81], v[36:37], v[128:129], v[80:81]
	v_pk_fma_f32 v[82:83], v[38:39], v[126:127], v[82:83]
	v_pk_fma_f32 v[84:85], v[28:29], v[118:119], v[84:85]
	v_pk_fma_f32 v[86:87], v[30:31], v[116:117], v[86:87]
	v_pk_fma_f32 v[80:81], v[32:33], v[114:115], v[80:81]
	v_pk_fma_f32 v[82:83], v[34:35], v[112:113], v[82:83]
	v_pk_fma_f32 v[84:85], v[8:9], v[110:111], v[84:85]
	v_pk_fma_f32 v[86:87], v[10:11], v[108:109], v[86:87]
	v_mul_f32_e32 v90, 0xbfb8aa3b, v80
	v_mul_f32_e32 v91, 0xbfb8aa3b, v81
	v_mul_f32_e32 v94, 0xbfb8aa3b, v82
	v_mul_f32_e32 v95, 0xbfb8aa3b, v83
	v_mul_f32_e32 v98, 0xbfb8aa3b, v84
	v_mul_f32_e32 v99, 0xbfb8aa3b, v85
	v_mul_f32_e32 v102, 0xbfb8aa3b, v86
	v_mul_f32_e32 v103, 0xbfb8aa3b, v87
	v_exp_f32_e32 v90, v90
	v_exp_f32_e32 v91, v91
	v_exp_f32_e32 v94, v94
	v_exp_f32_e32 v95, v95
	v_exp_f32_e32 v98, v98
	v_exp_f32_e32 v99, v99
	v_exp_f32_e32 v102, v102
	v_exp_f32_e32 v103, v103
	v_add_f32_e32 v90, 1.0, v90
	v_add_f32_e32 v91, 1.0, v91
	v_add_f32_e32 v94, 1.0, v94
	v_add_f32_e32 v95, 1.0, v95
	v_add_f32_e32 v98, 1.0, v98
	v_add_f32_e32 v99, 1.0, v99
	v_add_f32_e32 v102, 1.0, v102
	v_add_f32_e32 v103, 1.0, v103
	v_rcp_f32_e32 v90, v90
	v_rcp_f32_e32 v91, v91
	v_rcp_f32_e32 v94, v94
	v_rcp_f32_e32 v95, v95
	v_rcp_f32_e32 v98, v98
	v_rcp_f32_e32 v99, v99
	v_rcp_f32_e32 v102, v102
	v_rcp_f32_e32 v103, v103
	v_pk_mul_f32 v[80:81], v[80:81], v[90:91]
	v_pk_mul_f32 v[82:83], v[82:83], v[94:95]
	v_pk_mul_f32 v[84:85], v[84:85], v[98:99]
	v_pk_mul_f32 v[86:87], v[86:87], v[102:103]
	s_and_saveexec_b64 s[24:25], vcc
	s_cbranch_execz .LBB0_323
	v_pk_mul_f32 v[90:91], v[80:81], v[80:81]
	v_pk_mul_f32 v[94:95], v[82:83], v[82:83]
	v_add_f32_e32 v90, v90, v91
	v_add_f32_e32 v90, v94, v90
	v_pk_mul_f32 v[98:99], v[84:85], v[84:85]
	v_add_f32_e32 v90, v95, v90
	v_and_b32_e32 v94, 64, v158
	v_add_f32_e32 v90, v98, v90
	v_xor_b32_e32 v91, 1, v158
	v_add_u32_e32 v94, 64, v94
	v_pk_mul_f32 v[102:103], v[86:87], v[86:87]
	v_add_f32_e32 v90, v99, v90
	v_cmp_lt_i32_e64 s[4:5], v91, v94
	v_add_f32_e32 v90, v102, v90
	v_add_f32_e32 v90, v103, v90
	v_cndmask_b32_e64 v91, v158, v91, s[4:5]
	v_lshlrev_b32_e32 v91, 2, v91
	s_nop 1
	v_mov_b32_dpp v91, v90 quad_perm:[1,0,3,2] row_mask:0xf bank_mask:0xf
	v_add_f32_e32 v90, v90, v91
	v_xor_b32_e32 v91, 2, v158
	v_cmp_lt_i32_e64 s[4:5], v91, v94
	s_nop 1
	v_cndmask_b32_e64 v91, v158, v91, s[4:5]
	v_lshlrev_b32_e32 v91, 2, v91
	s_nop 1
	v_mov_b32_dpp v91, v90 quad_perm:[2,3,0,1] row_mask:0xf bank_mask:0xf
	v_add_f32_e32 v90, v90, v91
	v_xor_b32_e32 v91, 4, v158
	v_cmp_lt_i32_e64 s[4:5], v91, v94
	s_nop 1
	v_cndmask_b32_e64 v91, v158, v91, s[4:5]
	v_lshlrev_b32_e32 v91, 2, v91
	s_nop 1
	v_mov_b32_dpp v91, v90 row_half_mirror row_mask:0xf bank_mask:0xf
	v_add_f32_e32 v90, v90, v91
	v_xor_b32_e32 v91, 8, v158
	v_cmp_lt_i32_e64 s[4:5], v91, v94
	s_nop 1
	v_cndmask_b32_e64 v91, v158, v91, s[4:5]
	v_lshlrev_b32_e32 v91, 2, v91
	s_nop 1
	v_mov_b32_dpp v91, v90 row_ror:8 row_mask:0xf bank_mask:0xf
	v_add_f32_e32 v90, v90, v91
	v_add_f32_e32 v90, 0x358637bd, v90
	v_mul_f32_e32 v91, 0x4b800000, v90
	v_cmp_gt_f32_e64 s[4:5], s46, v90
	s_nop 1
	v_cndmask_b32_e64 v90, v90, v91, s[4:5]
	v_rsq_f32_e32 v90, v90
	s_nop 0
	v_mul_f32_e32 v91, 0x45800000, v90
	v_cndmask_b32_e64 v90, v90, v91, s[4:5]
	v_mul_f32_e32 v90, v157, v90
	v_pk_mul_f32 v[86:87], v[86:87], v[90:91] op_sel_hi:[1,0]
	v_pk_mul_f32 v[84:85], v[84:85], v[90:91] op_sel_hi:[1,0]
	v_pk_mul_f32 v[82:83], v[82:83], v[90:91] op_sel_hi:[1,0]
	v_pk_mul_f32 v[80:81], v[80:81], v[90:91] op_sel_hi:[1,0]
; DI unsigned pk2(float a, float b) { f32x2 v = {a, b}; bf16x2_t r = __builtin_convertvector(v, bf16x2_t); return __builtin_bit_cast(unsigned, r); }
; DI float bflo(unsigned u) { return __uint_as_float(u << 16); }
; DI float bfhi(unsigned u) { return __uint_as_float(u & 0xffff0000u); }
; DI float siluf_(float x) { return x * __builtin_amdgcn_rcpf(1.f + __expf(-x)); }
; DI void dn_conv_phase(const Params& p) {
;     ...
;         for (int tt = 0; tt < SEG; ++tt) {
;             { const u32x4 u = rows[tt + 4]; const int sl = (tt + 4) % 5;
;               ring[sl][0] = (f32x2){bflo(u.x), bfhi(u.x)}; ring[sl][1] = (f32x2){bflo(u.y), bfhi(u.y)}; ring[sl][2] = (f32x2){bflo(u.z), bfhi(u.z)}; ring[sl][3] = (f32x2){bflo(u.w), bfhi(u.w)}; }
;             f32x2 o2[4];
; #pragma unroll
;             for (int e = 0; e < 4; ++e) o2[e] = w[0][e] * ring[tt % 5][e];
; #pragma unroll
;             for (int j = 1; j < 5; ++j)
; #pragma unroll
;                 for (int e = 0; e < 4; ++e) o2[e] += w[j][e] * ring[(tt + j) % 5][e];
;             float o[8];
; #pragma unroll
;             for (int e = 0; e < 4; ++e) { o[2 * e] = siluf_(o2[e].x); o[2 * e + 1] = siluf_(o2[e].y); }
;             if (part < 2) {
;                 float ss = 0.f;
; #pragma unroll
;                 for (int e = 0; e < 8; ++e) ss += o[e] * o[e];
;                 ss += __shfl_xor(ss, 1); ss += __shfl_xor(ss, 2); ss += __shfl_xor(ss, 4); ss += __shfl_xor(ss, 8);
;                 const float sc = rsqrtf(ss + EPS) * (part == 0 ? 0.08838834764831845f : 1.f);
; #pragma unroll
;                 for (int e = 0; e < 8; ++e) o[e] *= sc;
;             }
;             u32x4 ov; ov.x = pk2(o[0], o[1]); ov.y = pk2(o[2], o[3]); ov.z = pk2(o[4], o[5]); ov.w = pk2(o[6], o[7]);
;             *(u32x4*)(QKV + (size_t)(row0 + tt) * 1536 + ch) = ov;
.LBB0_323:
	s_or_b64 exec, exec, s[24:25]
	v_cvt_pk_bf16_f32 v80, v80, v81
	v_cvt_pk_bf16_f32 v81, v82, v83
	v_cvt_pk_bf16_f32 v82, v84, v85
	v_or_b32_e32 v84, 5, v156
	v_cvt_pk_bf16_f32 v83, v86, v87
	v_mad_i64_i32 v[84:85], s[4:5], v84, s45, v[100:101]
	global_store_dwordx4 v[84:85], v[80:83], off
	v_lshlrev_b32_e32 v106, 16, v76
	v_and_b32_e32 v107, 0xffff0000, v76
	v_lshlrev_b32_e32 v104, 16, v77
	v_and_b32_e32 v105, 0xffff0000, v77
	v_lshlrev_b32_e32 v102, 16, v78
	v_and_b32_e32 v103, 0xffff0000, v78
	v_lshlrev_b32_e32 v98, 16, v79
	v_and_b32_e32 v99, 0xffff0000, v79
	v_pk_mul_f32 v[76:77], v[20:21], v[134:135]
	v_pk_mul_f32 v[78:79], v[22:23], v[132:133]
	v_pk_mul_f32 v[80:81], v[12:13], v[130:131]
	v_pk_mul_f32 v[82:83], v[14:15], v[88:89]
	v_pk_fma_f32 v[76:77], v[4:5], v[138:139], v[76:77]
	v_pk_fma_f32 v[78:79], v[6:7], v[136:137], v[78:79]
	v_pk_fma_f32 v[80:81], v[0:1], v[96:97], v[80:81]
	v_pk_fma_f32 v[82:83], v[2:3], v[92:93], v[82:83]
	v_pk_fma_f32 v[76:77], v[24:25], v[128:129], v[76:77]
	v_pk_fma_f32 v[78:79], v[26:27], v[126:127], v[78:79]
	v_pk_fma_f32 v[80:81], v[16:17], v[118:119], v[80:81]
	v_pk_fma_f32 v[82:83], v[18:19], v[116:117], v[82:83]
	v_pk_fma_f32 v[76:77], v[36:37], v[114:115], v[76:77]
	v_pk_fma_f32 v[78:79], v[38:39], v[112:113], v[78:79]
	v_pk_fma_f32 v[80:81], v[28:29], v[110:111], v[80:81]
	v_pk_fma_f32 v[82:83], v[30:31], v[108:109], v[82:83]
	v_pk_fma_f32 v[76:77], v[32:33], v[106:107], v[76:77]
	v_pk_fma_f32 v[78:79], v[34:35], v[104:105], v[78:79]
	v_pk_fma_f32 v[80:81], v[8:9], v[102:103], v[80:81]
	v_pk_fma_f32 v[82:83], v[10:11], v[98:99], v[82:83]
	v_mul_f32_e32 v84, 0xbfb8aa3b, v76
	v_mul_f32_e32 v85, 0xbfb8aa3b, v77
	v_mul_f32_e32 v86, 0xbfb8aa3b, v78
	v_mul_f32_e32 v87, 0xbfb8aa3b, v79
	v_mul_f32_e32 v90, 0xbfb8aa3b, v80
	v_mul_f32_e32 v91, 0xbfb8aa3b, v81
	v_mul_f32_e32 v92, 0xbfb8aa3b, v82
	v_mul_f32_e32 v93, 0xbfb8aa3b, v83
	v_exp_f32_e32 v84, v84
	v_exp_f32_e32 v85, v85
	v_exp_f32_e32 v86, v86
	v_exp_f32_e32 v87, v87
	v_exp_f32_e32 v90, v90
	v_exp_f32_e32 v91, v91
	v_exp_f32_e32 v92, v92
	v_exp_f32_e32 v93, v93
	v_add_f32_e32 v84, 1.0, v84
	v_add_f32_e32 v85, 1.0, v85
	v_add_f32_e32 v86, 1.0, v86
	v_add_f32_e32 v87, 1.0, v87
	v_add_f32_e32 v90, 1.0, v90
	v_add_f32_e32 v91, 1.0, v91
	v_add_f32_e32 v92, 1.0, v92
	v_add_f32_e32 v93, 1.0, v93
	v_rcp_f32_e32 v84, v84
	v_rcp_f32_e32 v85, v85
	v_rcp_f32_e32 v86, v86
	v_rcp_f32_e32 v87, v87
	v_rcp_f32_e32 v90, v90
	v_rcp_f32_e32 v91, v91
	v_rcp_f32_e32 v92, v92
	v_rcp_f32_e32 v93, v93
	v_pk_mul_f32 v[76:77], v[76:77], v[84:85]
	v_pk_mul_f32 v[78:79], v[78:79], v[86:87]
	v_pk_mul_f32 v[80:81], v[80:81], v[90:91]
	v_pk_mul_f32 v[82:83], v[82:83], v[92:93]
	s_and_saveexec_b64 s[24:25], vcc
	s_cbranch_execz .LBB0_325
	v_pk_mul_f32 v[84:85], v[76:77], v[76:77]
	v_pk_mul_f32 v[86:87], v[78:79], v[78:79]
	v_add_f32_e32 v84, v84, v85
	v_add_f32_e32 v84, v86, v84
	v_pk_mul_f32 v[90:91], v[80:81], v[80:81]
	v_add_f32_e32 v84, v87, v84
	v_and_b32_e32 v86, 64, v158
	v_add_f32_e32 v84, v90, v84
	v_xor_b32_e32 v85, 1, v158
	v_add_u32_e32 v86, 64, v86
	v_pk_mul_f32 v[92:93], v[82:83], v[82:83]
	v_add_f32_e32 v84, v91, v84
	v_cmp_lt_i32_e64 s[4:5], v85, v86
	v_add_f32_e32 v84, v92, v84
	v_add_f32_e32 v84, v93, v84
	v_cndmask_b32_e64 v85, v158, v85, s[4:5]
	v_lshlrev_b32_e32 v85, 2, v85
	s_nop 1
	v_mov_b32_dpp v85, v84 quad_perm:[1,0,3,2] row_mask:0xf bank_mask:0xf
	v_add_f32_e32 v84, v84, v85
	v_xor_b32_e32 v85, 2, v158
	v_cmp_lt_i32_e64 s[4:5], v85, v86
	s_nop 1
	v_cndmask_b32_e64 v85, v158, v85, s[4:5]
	v_lshlrev_b32_e32 v85, 2, v85
	s_nop 1
	v_mov_b32_dpp v85, v84 quad_perm:[2,3,0,1] row_mask:0xf bank_mask:0xf
	v_add_f32_e32 v84, v84, v85
	v_xor_b32_e32 v85, 4, v158
	v_cmp_lt_i32_e64 s[4:5], v85, v86
	s_nop 1
	v_cndmask_b32_e64 v85, v158, v85, s[4:5]
	v_lshlrev_b32_e32 v85, 2, v85
	s_nop 1
	v_mov_b32_dpp v85, v84 row_half_mirror row_mask:0xf bank_mask:0xf
	v_add_f32_e32 v84, v84, v85
	v_xor_b32_e32 v85, 8, v158
	v_cmp_lt_i32_e64 s[4:5], v85, v86
	s_nop 1
	v_cndmask_b32_e64 v85, v158, v85, s[4:5]
	v_lshlrev_b32_e32 v85, 2, v85
	s_nop 1
	v_mov_b32_dpp v85, v84 row_ror:8 row_mask:0xf bank_mask:0xf
	v_add_f32_e32 v84, v84, v85
	v_add_f32_e32 v84, 0x358637bd, v84
	v_mul_f32_e32 v85, 0x4b800000, v84
	v_cmp_gt_f32_e64 s[4:5], s46, v84
	s_nop 1
	v_cndmask_b32_e64 v84, v84, v85, s[4:5]
	v_rsq_f32_e32 v84, v84
	s_nop 0
	v_mul_f32_e32 v85, 0x45800000, v84
	v_cndmask_b32_e64 v84, v84, v85, s[4:5]
	v_mul_f32_e32 v84, v157, v84
	v_pk_mul_f32 v[82:83], v[82:83], v[84:85] op_sel_hi:[1,0]
	v_pk_mul_f32 v[80:81], v[80:81], v[84:85] op_sel_hi:[1,0]
	v_pk_mul_f32 v[78:79], v[78:79], v[84:85] op_sel_hi:[1,0]
	v_pk_mul_f32 v[76:77], v[76:77], v[84:85] op_sel_hi:[1,0]
; DI unsigned pk2(float a, float b) { f32x2 v = {a, b}; bf16x2_t r = __builtin_convertvector(v, bf16x2_t); return __builtin_bit_cast(unsigned, r); }
; DI float bflo(unsigned u) { return __uint_as_float(u << 16); }
; DI float bfhi(unsigned u) { return __uint_as_float(u & 0xffff0000u); }
; DI float siluf_(float x) { return x * __builtin_amdgcn_rcpf(1.f + __expf(-x)); }
; DI void dn_conv_phase(const Params& p) {
;     ...
;         for (int tt = 0; tt < SEG; ++tt) {
;             { const u32x4 u = rows[tt + 4]; const int sl = (tt + 4) % 5;
;               ring[sl][0] = (f32x2){bflo(u.x), bfhi(u.x)}; ring[sl][1] = (f32x2){bflo(u.y), bfhi(u.y)}; ring[sl][2] = (f32x2){bflo(u.z), bfhi(u.z)}; ring[sl][3] = (f32x2){bflo(u.w), bfhi(u.w)}; }
;             f32x2 o2[4];
; #pragma unroll
;             for (int e = 0; e < 4; ++e) o2[e] = w[0][e] * ring[tt % 5][e];
; #pragma unroll
;             for (int j = 1; j < 5; ++j)
; #pragma unroll
;                 for (int e = 0; e < 4; ++e) o2[e] += w[j][e] * ring[(tt + j) % 5][e];
;             float o[8];
; #pragma unroll
;             for (int e = 0; e < 4; ++e) { o[2 * e] = siluf_(o2[e].x); o[2 * e + 1] = siluf_(o2[e].y); }
;             if (part < 2) {
;                 float ss = 0.f;
; #pragma unroll
;                 for (int e = 0; e < 8; ++e) ss += o[e] * o[e];
;                 ss += __shfl_xor(ss, 1); ss += __shfl_xor(ss, 2); ss += __shfl_xor(ss, 4); ss += __shfl_xor(ss, 8);
;                 const float sc = rsqrtf(ss + EPS) * (part == 0 ? 0.08838834764831845f : 1.f);
; #pragma unroll
;                 for (int e = 0; e < 8; ++e) o[e] *= sc;
;             }
;             u32x4 ov; ov.x = pk2(o[0], o[1]); ov.y = pk2(o[2], o[3]); ov.z = pk2(o[4], o[5]); ov.w = pk2(o[6], o[7]);
;             *(u32x4*)(QKV + (size_t)(row0 + tt) * 1536 + ch) = ov;
.LBB0_325:
	s_or_b64 exec, exec, s[24:25]
	v_cvt_pk_bf16_f32 v76, v76, v77
	v_cvt_pk_bf16_f32 v77, v78, v79
	v_cvt_pk_bf16_f32 v78, v80, v81
	v_or_b32_e32 v80, 6, v156
	v_cvt_pk_bf16_f32 v79, v82, v83
	v_mad_i64_i32 v[80:81], s[4:5], v80, s45, v[100:101]
	global_store_dwordx4 v[80:81], v[76:79], off
	v_lshlrev_b32_e32 v96, 16, v72
	v_and_b32_e32 v97, 0xffff0000, v72
	v_lshlrev_b32_e32 v94, 16, v73
	v_and_b32_e32 v95, 0xffff0000, v73
	v_lshlrev_b32_e32 v92, 16, v74
	v_and_b32_e32 v93, 0xffff0000, v74
	v_lshlrev_b32_e32 v90, 16, v75
	v_and_b32_e32 v91, 0xffff0000, v75
	v_pk_mul_f32 v[72:73], v[20:21], v[128:129]
	v_pk_mul_f32 v[74:75], v[22:23], v[126:127]
	v_pk_mul_f32 v[76:77], v[12:13], v[118:119]
	v_pk_mul_f32 v[78:79], v[14:15], v[116:117]
	v_pk_fma_f32 v[72:73], v[4:5], v[134:135], v[72:73]
	v_pk_fma_f32 v[74:75], v[6:7], v[132:133], v[74:75]
	v_pk_fma_f32 v[76:77], v[0:1], v[130:131], v[76:77]
	v_pk_fma_f32 v[78:79], v[2:3], v[88:89], v[78:79]
	v_pk_fma_f32 v[72:73], v[24:25], v[114:115], v[72:73]
	v_pk_fma_f32 v[74:75], v[26:27], v[112:113], v[74:75]
	v_pk_fma_f32 v[76:77], v[16:17], v[110:111], v[76:77]
	v_pk_fma_f32 v[78:79], v[18:19], v[108:109], v[78:79]
	v_pk_fma_f32 v[72:73], v[36:37], v[106:107], v[72:73]
	v_pk_fma_f32 v[74:75], v[38:39], v[104:105], v[74:75]
	v_pk_fma_f32 v[76:77], v[28:29], v[102:103], v[76:77]
	v_pk_fma_f32 v[78:79], v[30:31], v[98:99], v[78:79]
	v_pk_fma_f32 v[72:73], v[32:33], v[96:97], v[72:73]
	v_pk_fma_f32 v[74:75], v[34:35], v[94:95], v[74:75]
	v_pk_fma_f32 v[76:77], v[8:9], v[92:93], v[76:77]
	v_pk_fma_f32 v[78:79], v[10:11], v[90:91], v[78:79]
	v_mul_f32_e32 v80, 0xbfb8aa3b, v72
	v_mul_f32_e32 v81, 0xbfb8aa3b, v73
	v_mul_f32_e32 v82, 0xbfb8aa3b, v74
	v_mul_f32_e32 v83, 0xbfb8aa3b, v75
	v_mul_f32_e32 v84, 0xbfb8aa3b, v76
	v_mul_f32_e32 v85, 0xbfb8aa3b, v77
	v_mul_f32_e32 v86, 0xbfb8aa3b, v78
	v_mul_f32_e32 v87, 0xbfb8aa3b, v79
	v_exp_f32_e32 v80, v80
	v_exp_f32_e32 v81, v81
	v_exp_f32_e32 v82, v82
	v_exp_f32_e32 v83, v83
	v_exp_f32_e32 v84, v84
	v_exp_f32_e32 v85, v85
	v_exp_f32_e32 v86, v86
	v_exp_f32_e32 v87, v87
	v_add_f32_e32 v80, 1.0, v80
	v_add_f32_e32 v81, 1.0, v81
	v_add_f32_e32 v82, 1.0, v82
	v_add_f32_e32 v83, 1.0, v83
	v_add_f32_e32 v84, 1.0, v84
	v_add_f32_e32 v85, 1.0, v85
	v_add_f32_e32 v86, 1.0, v86
	v_add_f32_e32 v87, 1.0, v87
	v_rcp_f32_e32 v80, v80
	v_rcp_f32_e32 v81, v81
	v_rcp_f32_e32 v82, v82
	v_rcp_f32_e32 v83, v83
	v_rcp_f32_e32 v84, v84
	v_rcp_f32_e32 v85, v85
	v_rcp_f32_e32 v86, v86
	v_rcp_f32_e32 v87, v87
	v_pk_mul_f32 v[72:73], v[72:73], v[80:81]
	v_pk_mul_f32 v[74:75], v[74:75], v[82:83]
	v_pk_mul_f32 v[76:77], v[76:77], v[84:85]
	v_pk_mul_f32 v[78:79], v[78:79], v[86:87]
	s_and_saveexec_b64 s[24:25], vcc
	s_cbranch_execz .LBB0_327
	v_pk_mul_f32 v[80:81], v[72:73], v[72:73]
	v_pk_mul_f32 v[82:83], v[74:75], v[74:75]
	v_add_f32_e32 v80, v80, v81
	v_add_f32_e32 v80, v82, v80
	v_pk_mul_f32 v[84:85], v[76:77], v[76:77]
	v_add_f32_e32 v80, v83, v80
	v_and_b32_e32 v82, 64, v158
	v_add_f32_e32 v80, v84, v80
	v_xor_b32_e32 v81, 1, v158
	v_add_u32_e32 v82, 64, v82
	v_pk_mul_f32 v[86:87], v[78:79], v[78:79]
	v_add_f32_e32 v80, v85, v80
	v_cmp_lt_i32_e64 s[4:5], v81, v82
	v_add_f32_e32 v80, v86, v80
	v_add_f32_e32 v80, v87, v80
	v_cndmask_b32_e64 v81, v158, v81, s[4:5]
	v_lshlrev_b32_e32 v81, 2, v81
	s_nop 1
	v_mov_b32_dpp v81, v80 quad_perm:[1,0,3,2] row_mask:0xf bank_mask:0xf
	v_add_f32_e32 v80, v80, v81
	v_xor_b32_e32 v81, 2, v158
	v_cmp_lt_i32_e64 s[4:5], v81, v82
	s_nop 1
	v_cndmask_b32_e64 v81, v158, v81, s[4:5]
	v_lshlrev_b32_e32 v81, 2, v81
	s_nop 1
	v_mov_b32_dpp v81, v80 quad_perm:[2,3,0,1] row_mask:0xf bank_mask:0xf
	v_add_f32_e32 v80, v80, v81
	v_xor_b32_e32 v81, 4, v158
	v_cmp_lt_i32_e64 s[4:5], v81, v82
	s_nop 1
	v_cndmask_b32_e64 v81, v158, v81, s[4:5]
	v_lshlrev_b32_e32 v81, 2, v81
	s_nop 1
	v_mov_b32_dpp v81, v80 row_half_mirror row_mask:0xf bank_mask:0xf
	v_add_f32_e32 v80, v80, v81
	v_xor_b32_e32 v81, 8, v158
	v_cmp_lt_i32_e64 s[4:5], v81, v82
	s_nop 1
	v_cndmask_b32_e64 v81, v158, v81, s[4:5]
	v_lshlrev_b32_e32 v81, 2, v81
	s_nop 1
	v_mov_b32_dpp v81, v80 row_ror:8 row_mask:0xf bank_mask:0xf
	v_add_f32_e32 v80, v80, v81
	v_add_f32_e32 v80, 0x358637bd, v80
	v_mul_f32_e32 v81, 0x4b800000, v80
	v_cmp_gt_f32_e64 s[4:5], s46, v80
	s_nop 1
	v_cndmask_b32_e64 v80, v80, v81, s[4:5]
	v_rsq_f32_e32 v80, v80
	s_nop 0
	v_mul_f32_e32 v81, 0x45800000, v80
	v_cndmask_b32_e64 v80, v80, v81, s[4:5]
	v_mul_f32_e32 v80, v157, v80
	v_pk_mul_f32 v[78:79], v[78:79], v[80:81] op_sel_hi:[1,0]
	v_pk_mul_f32 v[76:77], v[76:77], v[80:81] op_sel_hi:[1,0]
	v_pk_mul_f32 v[74:75], v[74:75], v[80:81] op_sel_hi:[1,0]
	v_pk_mul_f32 v[72:73], v[72:73], v[80:81] op_sel_hi:[1,0]
; DI unsigned pk2(float a, float b) { f32x2 v = {a, b}; bf16x2_t r = __builtin_convertvector(v, bf16x2_t); return __builtin_bit_cast(unsigned, r); }
; DI float bflo(unsigned u) { return __uint_as_float(u << 16); }
; DI float bfhi(unsigned u) { return __uint_as_float(u & 0xffff0000u); }
; DI float siluf_(float x) { return x * __builtin_amdgcn_rcpf(1.f + __expf(-x)); }
; DI void dn_conv_phase(const Params& p) {
;     ...
;         for (int tt = 0; tt < SEG; ++tt) {
;             { const u32x4 u = rows[tt + 4]; const int sl = (tt + 4) % 5;
;               ring[sl][0] = (f32x2){bflo(u.x), bfhi(u.x)}; ring[sl][1] = (f32x2){bflo(u.y), bfhi(u.y)}; ring[sl][2] = (f32x2){bflo(u.z), bfhi(u.z)}; ring[sl][3] = (f32x2){bflo(u.w), bfhi(u.w)}; }
;             f32x2 o2[4];
; #pragma unroll
;             for (int e = 0; e < 4; ++e) o2[e] = w[0][e] * ring[tt % 5][e];
; #pragma unroll
;             for (int j = 1; j < 5; ++j)
; #pragma unroll
;                 for (int e = 0; e < 4; ++e) o2[e] += w[j][e] * ring[(tt + j) % 5][e];
;             float o[8];
; #pragma unroll
;             for (int e = 0; e < 4; ++e) { o[2 * e] = siluf_(o2[e].x); o[2 * e + 1] = siluf_(o2[e].y); }
;             if (part < 2) {
;                 float ss = 0.f;
; #pragma unroll
;                 for (int e = 0; e < 8; ++e) ss += o[e] * o[e];
;                 ss += __shfl_xor(ss, 1); ss += __shfl_xor(ss, 2); ss += __shfl_xor(ss, 4); ss += __shfl_xor(ss, 8);
;                 const float sc = rsqrtf(ss + EPS) * (part == 0 ? 0.08838834764831845f : 1.f);
; #pragma unroll
;                 for (int e = 0; e < 8; ++e) o[e] *= sc;
;             }
;             u32x4 ov; ov.x = pk2(o[0], o[1]); ov.y = pk2(o[2], o[3]); ov.z = pk2(o[4], o[5]); ov.w = pk2(o[6], o[7]);
;             *(u32x4*)(QKV + (size_t)(row0 + tt) * 1536 + ch) = ov;
.LBB0_327:
	s_or_b64 exec, exec, s[24:25]
	v_cvt_pk_bf16_f32 v72, v72, v73
	v_cvt_pk_bf16_f32 v73, v74, v75
	v_cvt_pk_bf16_f32 v74, v76, v77
	v_or_b32_e32 v76, 7, v156
	v_cvt_pk_bf16_f32 v75, v78, v79
	v_mad_i64_i32 v[76:77], s[4:5], v76, s45, v[100:101]
	global_store_dwordx4 v[76:77], v[72:75], off
	v_lshlrev_b32_e32 v88, 16, v68
	v_and_b32_e32 v89, 0xffff0000, v68
	v_lshlrev_b32_e32 v86, 16, v69
	v_and_b32_e32 v87, 0xffff0000, v69
	v_lshlrev_b32_e32 v84, 16, v70
	v_and_b32_e32 v85, 0xffff0000, v70
	v_lshlrev_b32_e32 v82, 16, v71
	v_and_b32_e32 v83, 0xffff0000, v71
	v_pk_mul_f32 v[68:69], v[20:21], v[114:115]
	v_pk_mul_f32 v[70:71], v[22:23], v[112:113]
	v_pk_mul_f32 v[72:73], v[12:13], v[110:111]
	v_pk_mul_f32 v[74:75], v[14:15], v[108:109]
	v_pk_fma_f32 v[68:69], v[4:5], v[128:129], v[68:69]
	v_pk_fma_f32 v[70:71], v[6:7], v[126:127], v[70:71]
	v_pk_fma_f32 v[72:73], v[0:1], v[118:119], v[72:73]
	v_pk_fma_f32 v[74:75], v[2:3], v[116:117], v[74:75]
	v_pk_fma_f32 v[68:69], v[24:25], v[106:107], v[68:69]
	v_pk_fma_f32 v[70:71], v[26:27], v[104:105], v[70:71]
	v_pk_fma_f32 v[72:73], v[16:17], v[102:103], v[72:73]
	v_pk_fma_f32 v[74:75], v[18:19], v[98:99], v[74:75]
	v_pk_fma_f32 v[68:69], v[36:37], v[96:97], v[68:69]
	v_pk_fma_f32 v[70:71], v[38:39], v[94:95], v[70:71]
	v_pk_fma_f32 v[72:73], v[28:29], v[92:93], v[72:73]
	v_pk_fma_f32 v[74:75], v[30:31], v[90:91], v[74:75]
	v_pk_fma_f32 v[68:69], v[32:33], v[88:89], v[68:69]
	v_pk_fma_f32 v[70:71], v[34:35], v[86:87], v[70:71]
	v_pk_fma_f32 v[72:73], v[8:9], v[84:85], v[72:73]
	v_pk_fma_f32 v[74:75], v[10:11], v[82:83], v[74:75]
	v_mul_f32_e32 v76, 0xbfb8aa3b, v68
	v_mul_f32_e32 v77, 0xbfb8aa3b, v69
	v_mul_f32_e32 v78, 0xbfb8aa3b, v70
	v_mul_f32_e32 v79, 0xbfb8aa3b, v71
	v_mul_f32_e32 v80, 0xbfb8aa3b, v72
	v_mul_f32_e32 v81, 0xbfb8aa3b, v73
	v_mul_f32_e32 v116, 0xbfb8aa3b, v74
	v_mul_f32_e32 v117, 0xbfb8aa3b, v75
	v_exp_f32_e32 v76, v76
	v_exp_f32_e32 v77, v77
	v_exp_f32_e32 v78, v78
	v_exp_f32_e32 v79, v79
	v_exp_f32_e32 v80, v80
	v_exp_f32_e32 v81, v81
	v_exp_f32_e32 v116, v116
	v_exp_f32_e32 v117, v117
	v_add_f32_e32 v76, 1.0, v76
	v_add_f32_e32 v77, 1.0, v77
	v_add_f32_e32 v78, 1.0, v78
	v_add_f32_e32 v79, 1.0, v79
	v_add_f32_e32 v80, 1.0, v80
	v_add_f32_e32 v81, 1.0, v81
	v_add_f32_e32 v116, 1.0, v116
	v_add_f32_e32 v117, 1.0, v117
	v_rcp_f32_e32 v76, v76
	v_rcp_f32_e32 v77, v77
	v_rcp_f32_e32 v78, v78
	v_rcp_f32_e32 v79, v79
	v_rcp_f32_e32 v80, v80
	v_rcp_f32_e32 v81, v81
	v_rcp_f32_e32 v116, v116
	v_rcp_f32_e32 v117, v117
	v_pk_mul_f32 v[68:69], v[68:69], v[76:77]
	v_pk_mul_f32 v[70:71], v[70:71], v[78:79]
	v_pk_mul_f32 v[72:73], v[72:73], v[80:81]
	v_pk_mul_f32 v[74:75], v[74:75], v[116:117]
	s_and_saveexec_b64 s[24:25], vcc
	s_cbranch_execz .LBB0_329
	v_pk_mul_f32 v[76:77], v[68:69], v[68:69]
	v_pk_mul_f32 v[78:79], v[70:71], v[70:71]
	v_add_f32_e32 v76, v76, v77
	v_add_f32_e32 v76, v78, v76
	v_pk_mul_f32 v[80:81], v[72:73], v[72:73]
	v_add_f32_e32 v76, v79, v76
	v_and_b32_e32 v78, 64, v158
	v_add_f32_e32 v76, v80, v76
	v_xor_b32_e32 v77, 1, v158
	v_add_u32_e32 v78, 64, v78
	v_pk_mul_f32 v[116:117], v[74:75], v[74:75]
	v_add_f32_e32 v76, v81, v76
	v_cmp_lt_i32_e64 s[4:5], v77, v78
	v_add_f32_e32 v76, v116, v76
	v_add_f32_e32 v76, v117, v76
	v_cndmask_b32_e64 v77, v158, v77, s[4:5]
	v_lshlrev_b32_e32 v77, 2, v77
	s_nop 1
	v_mov_b32_dpp v77, v76 quad_perm:[1,0,3,2] row_mask:0xf bank_mask:0xf
	v_add_f32_e32 v76, v76, v77
	v_xor_b32_e32 v77, 2, v158
	v_cmp_lt_i32_e64 s[4:5], v77, v78
	s_nop 1
	v_cndmask_b32_e64 v77, v158, v77, s[4:5]
	v_lshlrev_b32_e32 v77, 2, v77
	s_nop 1
	v_mov_b32_dpp v77, v76 quad_perm:[2,3,0,1] row_mask:0xf bank_mask:0xf
	v_add_f32_e32 v76, v76, v77
	v_xor_b32_e32 v77, 4, v158
	v_cmp_lt_i32_e64 s[4:5], v77, v78
	s_nop 1
	v_cndmask_b32_e64 v77, v158, v77, s[4:5]
	v_lshlrev_b32_e32 v77, 2, v77
	s_nop 1
	v_mov_b32_dpp v77, v76 row_half_mirror row_mask:0xf bank_mask:0xf
	v_add_f32_e32 v76, v76, v77
	v_xor_b32_e32 v77, 8, v158
	v_cmp_lt_i32_e64 s[4:5], v77, v78
	s_nop 1
	v_cndmask_b32_e64 v77, v158, v77, s[4:5]
	v_lshlrev_b32_e32 v77, 2, v77
	s_nop 1
	v_mov_b32_dpp v77, v76 row_ror:8 row_mask:0xf bank_mask:0xf
	v_add_f32_e32 v76, v76, v77
	v_add_f32_e32 v76, 0x358637bd, v76
	v_mul_f32_e32 v77, 0x4b800000, v76
	v_cmp_gt_f32_e64 s[4:5], s46, v76
	s_nop 1
	v_cndmask_b32_e64 v76, v76, v77, s[4:5]
	v_rsq_f32_e32 v76, v76
	s_nop 0
	v_mul_f32_e32 v77, 0x45800000, v76
	v_cndmask_b32_e64 v76, v76, v77, s[4:5]
	v_mul_f32_e32 v76, v157, v76
	v_pk_mul_f32 v[74:75], v[74:75], v[76:77] op_sel_hi:[1,0]
	v_pk_mul_f32 v[72:73], v[72:73], v[76:77] op_sel_hi:[1,0]
	v_pk_mul_f32 v[70:71], v[70:71], v[76:77] op_sel_hi:[1,0]
	v_pk_mul_f32 v[68:69], v[68:69], v[76:77] op_sel_hi:[1,0]
; DI unsigned pk2(float a, float b) { f32x2 v = {a, b}; bf16x2_t r = __builtin_convertvector(v, bf16x2_t); return __builtin_bit_cast(unsigned, r); }
; DI float bflo(unsigned u) { return __uint_as_float(u << 16); }
; DI float bfhi(unsigned u) { return __uint_as_float(u & 0xffff0000u); }
; DI float siluf_(float x) { return x * __builtin_amdgcn_rcpf(1.f + __expf(-x)); }
; DI void dn_conv_phase(const Params& p) {
;     ...
;         for (int tt = 0; tt < SEG; ++tt) {
;             { const u32x4 u = rows[tt + 4]; const int sl = (tt + 4) % 5;
;               ring[sl][0] = (f32x2){bflo(u.x), bfhi(u.x)}; ring[sl][1] = (f32x2){bflo(u.y), bfhi(u.y)}; ring[sl][2] = (f32x2){bflo(u.z), bfhi(u.z)}; ring[sl][3] = (f32x2){bflo(u.w), bfhi(u.w)}; }
;             f32x2 o2[4];
; #pragma unroll
;             for (int e = 0; e < 4; ++e) o2[e] = w[0][e] * ring[tt % 5][e];
; #pragma unroll
;             for (int j = 1; j < 5; ++j)
; #pragma unroll
;                 for (int e = 0; e < 4; ++e) o2[e] += w[j][e] * ring[(tt + j) % 5][e];
;             float o[8];
; #pragma unroll
;             for (int e = 0; e < 4; ++e) { o[2 * e] = siluf_(o2[e].x); o[2 * e + 1] = siluf_(o2[e].y); }
;             if (part < 2) {
;                 float ss = 0.f;
; #pragma unroll
;                 for (int e = 0; e < 8; ++e) ss += o[e] * o[e];
;                 ss += __shfl_xor(ss, 1); ss += __shfl_xor(ss, 2); ss += __shfl_xor(ss, 4); ss += __shfl_xor(ss, 8);
;                 const float sc = rsqrtf(ss + EPS) * (part == 0 ? 0.08838834764831845f : 1.f);
; #pragma unroll
;                 for (int e = 0; e < 8; ++e) o[e] *= sc;
;             }
;             u32x4 ov; ov.x = pk2(o[0], o[1]); ov.y = pk2(o[2], o[3]); ov.z = pk2(o[4], o[5]); ov.w = pk2(o[6], o[7]);
;             *(u32x4*)(QKV + (size_t)(row0 + tt) * 1536 + ch) = ov;
.LBB0_329:
	s_or_b64 exec, exec, s[24:25]
	v_cvt_pk_bf16_f32 v68, v68, v69
	v_cvt_pk_bf16_f32 v69, v70, v71
	v_cvt_pk_bf16_f32 v70, v72, v73
	v_or_b32_e32 v72, 8, v156
	v_cvt_pk_bf16_f32 v71, v74, v75
	v_mad_i64_i32 v[72:73], s[4:5], v72, s45, v[100:101]
	global_store_dwordx4 v[72:73], v[68:71], off
	v_lshlrev_b32_e32 v80, 16, v64
	v_and_b32_e32 v81, 0xffff0000, v64
	v_lshlrev_b32_e32 v78, 16, v65
	v_and_b32_e32 v79, 0xffff0000, v65
	v_lshlrev_b32_e32 v76, 16, v66
	v_and_b32_e32 v77, 0xffff0000, v66
	v_lshlrev_b32_e32 v74, 16, v67
	v_and_b32_e32 v75, 0xffff0000, v67
	v_pk_mul_f32 v[64:65], v[20:21], v[106:107]
	v_pk_mul_f32 v[66:67], v[22:23], v[104:105]
	v_pk_mul_f32 v[68:69], v[12:13], v[102:103]
	v_pk_mul_f32 v[70:71], v[14:15], v[98:99]
	v_pk_fma_f32 v[64:65], v[4:5], v[114:115], v[64:65]
	v_pk_fma_f32 v[66:67], v[6:7], v[112:113], v[66:67]
	v_pk_fma_f32 v[68:69], v[0:1], v[110:111], v[68:69]
	v_pk_fma_f32 v[70:71], v[2:3], v[108:109], v[70:71]
	v_pk_fma_f32 v[64:65], v[24:25], v[96:97], v[64:65]
	v_pk_fma_f32 v[66:67], v[26:27], v[94:95], v[66:67]
	v_pk_fma_f32 v[68:69], v[16:17], v[92:93], v[68:69]
	v_pk_fma_f32 v[70:71], v[18:19], v[90:91], v[70:71]
	v_pk_fma_f32 v[64:65], v[36:37], v[88:89], v[64:65]
	v_pk_fma_f32 v[66:67], v[38:39], v[86:87], v[66:67]
	v_pk_fma_f32 v[68:69], v[28:29], v[84:85], v[68:69]
	v_pk_fma_f32 v[70:71], v[30:31], v[82:83], v[70:71]
	v_pk_fma_f32 v[64:65], v[32:33], v[80:81], v[64:65]
	v_pk_fma_f32 v[66:67], v[34:35], v[78:79], v[66:67]
	v_pk_fma_f32 v[68:69], v[8:9], v[76:77], v[68:69]
	v_pk_fma_f32 v[70:71], v[10:11], v[74:75], v[70:71]
	v_mul_f32_e32 v72, 0xbfb8aa3b, v64
	v_mul_f32_e32 v73, 0xbfb8aa3b, v65
	v_mul_f32_e32 v108, 0xbfb8aa3b, v66
	v_mul_f32_e32 v109, 0xbfb8aa3b, v67
	v_mul_f32_e32 v110, 0xbfb8aa3b, v68
	v_mul_f32_e32 v111, 0xbfb8aa3b, v69
	v_mul_f32_e32 v112, 0xbfb8aa3b, v70
	v_mul_f32_e32 v113, 0xbfb8aa3b, v71
	v_exp_f32_e32 v72, v72
	v_exp_f32_e32 v73, v73
	v_exp_f32_e32 v108, v108
	v_exp_f32_e32 v109, v109
	v_exp_f32_e32 v110, v110
	v_exp_f32_e32 v111, v111
	v_exp_f32_e32 v112, v112
	v_exp_f32_e32 v113, v113
	v_add_f32_e32 v72, 1.0, v72
	v_add_f32_e32 v73, 1.0, v73
	v_add_f32_e32 v108, 1.0, v108
	v_add_f32_e32 v109, 1.0, v109
	v_add_f32_e32 v110, 1.0, v110
	v_add_f32_e32 v111, 1.0, v111
	v_add_f32_e32 v112, 1.0, v112
	v_add_f32_e32 v113, 1.0, v113
	v_rcp_f32_e32 v72, v72
	v_rcp_f32_e32 v73, v73
	v_rcp_f32_e32 v108, v108
	v_rcp_f32_e32 v109, v109
	v_rcp_f32_e32 v110, v110
	v_rcp_f32_e32 v111, v111
	v_rcp_f32_e32 v112, v112
	v_rcp_f32_e32 v113, v113
	v_pk_mul_f32 v[64:65], v[64:65], v[72:73]
	v_pk_mul_f32 v[66:67], v[66:67], v[108:109]
	v_pk_mul_f32 v[68:69], v[68:69], v[110:111]
	v_pk_mul_f32 v[70:71], v[70:71], v[112:113]
	s_and_saveexec_b64 s[24:25], vcc
	s_cbranch_execz .LBB0_331
	v_pk_mul_f32 v[72:73], v[64:65], v[64:65]
	v_pk_mul_f32 v[108:109], v[66:67], v[66:67]
	v_add_f32_e32 v72, v72, v73
	v_add_f32_e32 v72, v108, v72
	v_pk_mul_f32 v[110:111], v[68:69], v[68:69]
	v_add_f32_e32 v72, v109, v72
	v_and_b32_e32 v108, 64, v158
	v_add_f32_e32 v72, v110, v72
	v_xor_b32_e32 v73, 1, v158
	v_add_u32_e32 v108, 64, v108
	v_pk_mul_f32 v[112:113], v[70:71], v[70:71]
	v_add_f32_e32 v72, v111, v72
	v_cmp_lt_i32_e64 s[4:5], v73, v108
	v_add_f32_e32 v72, v112, v72
	v_add_f32_e32 v72, v113, v72
	v_cndmask_b32_e64 v73, v158, v73, s[4:5]
	v_lshlrev_b32_e32 v73, 2, v73
	s_nop 1
	v_mov_b32_dpp v73, v72 quad_perm:[1,0,3,2] row_mask:0xf bank_mask:0xf
	v_add_f32_e32 v72, v72, v73
	v_xor_b32_e32 v73, 2, v158
	v_cmp_lt_i32_e64 s[4:5], v73, v108
	s_nop 1
	v_cndmask_b32_e64 v73, v158, v73, s[4:5]
	v_lshlrev_b32_e32 v73, 2, v73
	s_nop 1
	v_mov_b32_dpp v73, v72 quad_perm:[2,3,0,1] row_mask:0xf bank_mask:0xf
	v_add_f32_e32 v72, v72, v73
	v_xor_b32_e32 v73, 4, v158
	v_cmp_lt_i32_e64 s[4:5], v73, v108
	s_nop 1
	v_cndmask_b32_e64 v73, v158, v73, s[4:5]
	v_lshlrev_b32_e32 v73, 2, v73
	s_nop 1
	v_mov_b32_dpp v73, v72 row_half_mirror row_mask:0xf bank_mask:0xf
	v_add_f32_e32 v72, v72, v73
	v_xor_b32_e32 v73, 8, v158
	v_cmp_lt_i32_e64 s[4:5], v73, v108
	s_nop 1
	v_cndmask_b32_e64 v73, v158, v73, s[4:5]
	v_lshlrev_b32_e32 v73, 2, v73
	s_nop 1
	v_mov_b32_dpp v73, v72 row_ror:8 row_mask:0xf bank_mask:0xf
	v_add_f32_e32 v72, v72, v73
	v_add_f32_e32 v72, 0x358637bd, v72
	v_mul_f32_e32 v73, 0x4b800000, v72
	v_cmp_gt_f32_e64 s[4:5], s46, v72
	s_nop 1
	v_cndmask_b32_e64 v72, v72, v73, s[4:5]
	v_rsq_f32_e32 v72, v72
	s_nop 0
	v_mul_f32_e32 v73, 0x45800000, v72
	v_cndmask_b32_e64 v72, v72, v73, s[4:5]
	v_mul_f32_e32 v72, v157, v72
	v_pk_mul_f32 v[70:71], v[70:71], v[72:73] op_sel_hi:[1,0]
	v_pk_mul_f32 v[68:69], v[68:69], v[72:73] op_sel_hi:[1,0]
	v_pk_mul_f32 v[66:67], v[66:67], v[72:73] op_sel_hi:[1,0]
	v_pk_mul_f32 v[64:65], v[64:65], v[72:73] op_sel_hi:[1,0]
; DI unsigned pk2(float a, float b) { f32x2 v = {a, b}; bf16x2_t r = __builtin_convertvector(v, bf16x2_t); return __builtin_bit_cast(unsigned, r); }
; DI float bflo(unsigned u) { return __uint_as_float(u << 16); }
; DI float bfhi(unsigned u) { return __uint_as_float(u & 0xffff0000u); }
; DI float siluf_(float x) { return x * __builtin_amdgcn_rcpf(1.f + __expf(-x)); }
; DI void dn_conv_phase(const Params& p) {
;     ...
;         for (int tt = 0; tt < SEG; ++tt) {
;             { const u32x4 u = rows[tt + 4]; const int sl = (tt + 4) % 5;
;               ring[sl][0] = (f32x2){bflo(u.x), bfhi(u.x)}; ring[sl][1] = (f32x2){bflo(u.y), bfhi(u.y)}; ring[sl][2] = (f32x2){bflo(u.z), bfhi(u.z)}; ring[sl][3] = (f32x2){bflo(u.w), bfhi(u.w)}; }
;             f32x2 o2[4];
; #pragma unroll
;             for (int e = 0; e < 4; ++e) o2[e] = w[0][e] * ring[tt % 5][e];
; #pragma unroll
;             for (int j = 1; j < 5; ++j)
; #pragma unroll
;                 for (int e = 0; e < 4; ++e) o2[e] += w[j][e] * ring[(tt + j) % 5][e];
;             float o[8];
; #pragma unroll
;             for (int e = 0; e < 4; ++e) { o[2 * e] = siluf_(o2[e].x); o[2 * e + 1] = siluf_(o2[e].y); }
;             if (part < 2) {
;                 float ss = 0.f;
; #pragma unroll
;                 for (int e = 0; e < 8; ++e) ss += o[e] * o[e];
;                 ss += __shfl_xor(ss, 1); ss += __shfl_xor(ss, 2); ss += __shfl_xor(ss, 4); ss += __shfl_xor(ss, 8);
;                 const float sc = rsqrtf(ss + EPS) * (part == 0 ? 0.08838834764831845f : 1.f);
; #pragma unroll
;                 for (int e = 0; e < 8; ++e) o[e] *= sc;
;             }
;             u32x4 ov; ov.x = pk2(o[0], o[1]); ov.y = pk2(o[2], o[3]); ov.z = pk2(o[4], o[5]); ov.w = pk2(o[6], o[7]);
;             *(u32x4*)(QKV + (size_t)(row0 + tt) * 1536 + ch) = ov;
.LBB0_331:
	s_or_b64 exec, exec, s[24:25]
	v_cvt_pk_bf16_f32 v64, v64, v65
	v_cvt_pk_bf16_f32 v65, v66, v67
	v_cvt_pk_bf16_f32 v66, v68, v69
	v_or_b32_e32 v68, 9, v156
	v_cvt_pk_bf16_f32 v67, v70, v71
	v_mad_i64_i32 v[68:69], s[4:5], v68, s45, v[100:101]
	global_store_dwordx4 v[68:69], v[64:67], off
	v_lshlrev_b32_e32 v72, 16, v60
	v_and_b32_e32 v73, 0xffff0000, v60
	v_pk_mul_f32 v[64:65], v[12:13], v[92:93]
	v_lshlrev_b32_e32 v70, 16, v61
	v_and_b32_e32 v71, 0xffff0000, v61
	v_lshlrev_b32_e32 v68, 16, v62
	v_and_b32_e32 v69, 0xffff0000, v62
	v_lshlrev_b32_e32 v66, 16, v63
	v_and_b32_e32 v67, 0xffff0000, v63
	v_pk_mul_f32 v[60:61], v[20:21], v[96:97]
	v_pk_mul_f32 v[62:63], v[22:23], v[94:95]
	v_pk_fma_f32 v[64:65], v[0:1], v[102:103], v[64:65]
	v_pk_mul_f32 v[102:103], v[14:15], v[90:91]
	v_pk_fma_f32 v[60:61], v[4:5], v[106:107], v[60:61]
	v_pk_fma_f32 v[62:63], v[6:7], v[104:105], v[62:63]
	v_pk_fma_f32 v[98:99], v[2:3], v[98:99], v[102:103]
	v_pk_fma_f32 v[60:61], v[24:25], v[88:89], v[60:61]
	v_pk_fma_f32 v[62:63], v[26:27], v[86:87], v[62:63]
	v_pk_fma_f32 v[64:65], v[16:17], v[84:85], v[64:65]
	v_pk_fma_f32 v[98:99], v[18:19], v[82:83], v[98:99]
	v_pk_fma_f32 v[60:61], v[36:37], v[80:81], v[60:61]
	v_pk_fma_f32 v[62:63], v[38:39], v[78:79], v[62:63]
	v_pk_fma_f32 v[64:65], v[28:29], v[76:77], v[64:65]
	v_pk_fma_f32 v[98:99], v[30:31], v[74:75], v[98:99]
	v_pk_fma_f32 v[60:61], v[32:33], v[72:73], v[60:61]
	v_pk_fma_f32 v[62:63], v[34:35], v[70:71], v[62:63]
	v_pk_fma_f32 v[64:65], v[8:9], v[68:69], v[64:65]
	v_pk_fma_f32 v[98:99], v[10:11], v[66:67], v[98:99]
	v_mul_f32_e32 v102, 0xbfb8aa3b, v60
	v_mul_f32_e32 v103, 0xbfb8aa3b, v61
	v_mul_f32_e32 v104, 0xbfb8aa3b, v62
	v_mul_f32_e32 v105, 0xbfb8aa3b, v63
	v_mul_f32_e32 v106, 0xbfb8aa3b, v64
	v_mul_f32_e32 v107, 0xbfb8aa3b, v65
	v_mul_f32_e32 v108, 0xbfb8aa3b, v98
	v_mul_f32_e32 v109, 0xbfb8aa3b, v99
	v_exp_f32_e32 v102, v102
	v_exp_f32_e32 v103, v103
	v_exp_f32_e32 v104, v104
	v_exp_f32_e32 v105, v105
	v_exp_f32_e32 v106, v106
	v_exp_f32_e32 v107, v107
	v_exp_f32_e32 v108, v108
	v_exp_f32_e32 v109, v109
	v_add_f32_e32 v102, 1.0, v102
	v_add_f32_e32 v103, 1.0, v103
	v_add_f32_e32 v104, 1.0, v104
	v_add_f32_e32 v105, 1.0, v105
	v_add_f32_e32 v106, 1.0, v106
	v_add_f32_e32 v107, 1.0, v107
	v_add_f32_e32 v108, 1.0, v108
	v_add_f32_e32 v109, 1.0, v109
	v_rcp_f32_e32 v102, v102
	v_rcp_f32_e32 v103, v103
	v_rcp_f32_e32 v104, v104
	v_rcp_f32_e32 v105, v105
	v_rcp_f32_e32 v106, v106
	v_rcp_f32_e32 v107, v107
	v_rcp_f32_e32 v108, v108
	v_rcp_f32_e32 v109, v109
	v_pk_mul_f32 v[60:61], v[60:61], v[102:103]
	v_pk_mul_f32 v[62:63], v[62:63], v[104:105]
	v_pk_mul_f32 v[64:65], v[64:65], v[106:107]
	v_pk_mul_f32 v[98:99], v[98:99], v[108:109]
	s_and_saveexec_b64 s[24:25], vcc
	s_cbranch_execz .LBB0_333
	v_pk_mul_f32 v[102:103], v[60:61], v[60:61]
	v_pk_mul_f32 v[104:105], v[62:63], v[62:63]
	v_add_f32_e32 v102, v102, v103
	v_add_f32_e32 v102, v104, v102
	v_pk_mul_f32 v[106:107], v[64:65], v[64:65]
	v_add_f32_e32 v102, v105, v102
	v_and_b32_e32 v104, 64, v158
	v_add_f32_e32 v102, v106, v102
	v_xor_b32_e32 v103, 1, v158
	v_add_u32_e32 v104, 64, v104
	v_pk_mul_f32 v[108:109], v[98:99], v[98:99]
	v_add_f32_e32 v102, v107, v102
	v_cmp_lt_i32_e64 s[4:5], v103, v104
	v_add_f32_e32 v102, v108, v102
	v_add_f32_e32 v102, v109, v102
	v_cndmask_b32_e64 v103, v158, v103, s[4:5]
	v_lshlrev_b32_e32 v103, 2, v103
	s_nop 1
	v_mov_b32_dpp v103, v102 quad_perm:[1,0,3,2] row_mask:0xf bank_mask:0xf
	v_add_f32_e32 v102, v102, v103
	v_xor_b32_e32 v103, 2, v158
	v_cmp_lt_i32_e64 s[4:5], v103, v104
	s_nop 1
	v_cndmask_b32_e64 v103, v158, v103, s[4:5]
	v_lshlrev_b32_e32 v103, 2, v103
	s_nop 1
	v_mov_b32_dpp v103, v102 quad_perm:[2,3,0,1] row_mask:0xf bank_mask:0xf
	v_add_f32_e32 v102, v102, v103
	v_xor_b32_e32 v103, 4, v158
	v_cmp_lt_i32_e64 s[4:5], v103, v104
	s_nop 1
	v_cndmask_b32_e64 v103, v158, v103, s[4:5]
	v_lshlrev_b32_e32 v103, 2, v103
	s_nop 1
	v_mov_b32_dpp v103, v102 row_half_mirror row_mask:0xf bank_mask:0xf
	v_add_f32_e32 v102, v102, v103
	v_xor_b32_e32 v103, 8, v158
	v_cmp_lt_i32_e64 s[4:5], v103, v104
	s_nop 1
	v_cndmask_b32_e64 v103, v158, v103, s[4:5]
	v_lshlrev_b32_e32 v103, 2, v103
	s_nop 1
	v_mov_b32_dpp v103, v102 row_ror:8 row_mask:0xf bank_mask:0xf
	v_add_f32_e32 v102, v102, v103
	v_add_f32_e32 v102, 0x358637bd, v102
	v_mul_f32_e32 v103, 0x4b800000, v102
	v_cmp_gt_f32_e64 s[4:5], s46, v102
	s_nop 1
	v_cndmask_b32_e64 v102, v102, v103, s[4:5]
	v_rsq_f32_e32 v102, v102
	s_nop 0
	v_mul_f32_e32 v103, 0x45800000, v102
	v_cndmask_b32_e64 v102, v102, v103, s[4:5]
	v_mul_f32_e32 v102, v157, v102
	v_pk_mul_f32 v[98:99], v[98:99], v[102:103] op_sel_hi:[1,0]
	v_pk_mul_f32 v[64:65], v[64:65], v[102:103] op_sel_hi:[1,0]
	v_pk_mul_f32 v[62:63], v[62:63], v[102:103] op_sel_hi:[1,0]
	v_pk_mul_f32 v[60:61], v[60:61], v[102:103] op_sel_hi:[1,0]
; DI unsigned pk2(float a, float b) { f32x2 v = {a, b}; bf16x2_t r = __builtin_convertvector(v, bf16x2_t); return __builtin_bit_cast(unsigned, r); }
; DI float bflo(unsigned u) { return __uint_as_float(u << 16); }
; DI float bfhi(unsigned u) { return __uint_as_float(u & 0xffff0000u); }
; DI float siluf_(float x) { return x * __builtin_amdgcn_rcpf(1.f + __expf(-x)); }
; DI void dn_conv_phase(const Params& p) {
;     ...
;         for (int tt = 0; tt < SEG; ++tt) {
;             { const u32x4 u = rows[tt + 4]; const int sl = (tt + 4) % 5;
;               ring[sl][0] = (f32x2){bflo(u.x), bfhi(u.x)}; ring[sl][1] = (f32x2){bflo(u.y), bfhi(u.y)}; ring[sl][2] = (f32x2){bflo(u.z), bfhi(u.z)}; ring[sl][3] = (f32x2){bflo(u.w), bfhi(u.w)}; }
;             f32x2 o2[4];
; #pragma unroll
;             for (int e = 0; e < 4; ++e) o2[e] = w[0][e] * ring[tt % 5][e];
; #pragma unroll
;             for (int j = 1; j < 5; ++j)
; #pragma unroll
;                 for (int e = 0; e < 4; ++e) o2[e] += w[j][e] * ring[(tt + j) % 5][e];
;             float o[8];
; #pragma unroll
;             for (int e = 0; e < 4; ++e) { o[2 * e] = siluf_(o2[e].x); o[2 * e + 1] = siluf_(o2[e].y); }
;             if (part < 2) {
;                 float ss = 0.f;
; #pragma unroll
;                 for (int e = 0; e < 8; ++e) ss += o[e] * o[e];
;                 ss += __shfl_xor(ss, 1); ss += __shfl_xor(ss, 2); ss += __shfl_xor(ss, 4); ss += __shfl_xor(ss, 8);
;                 const float sc = rsqrtf(ss + EPS) * (part == 0 ? 0.08838834764831845f : 1.f);
; #pragma unroll
;                 for (int e = 0; e < 8; ++e) o[e] *= sc;
;             }
;             u32x4 ov; ov.x = pk2(o[0], o[1]); ov.y = pk2(o[2], o[3]); ov.z = pk2(o[4], o[5]); ov.w = pk2(o[6], o[7]);
;             *(u32x4*)(QKV + (size_t)(row0 + tt) * 1536 + ch) = ov;
.LBB0_333:
	s_or_b64 exec, exec, s[24:25]
	v_cvt_pk_bf16_f32 v60, v60, v61
	v_cvt_pk_bf16_f32 v61, v62, v63
	v_cvt_pk_bf16_f32 v62, v64, v65
	v_or_b32_e32 v64, 10, v156
	v_cvt_pk_bf16_f32 v63, v98, v99
	v_mad_i64_i32 v[64:65], s[4:5], v64, s45, v[100:101]
	global_store_dwordx4 v[64:65], v[60:63], off
	v_lshlrev_b32_e32 v64, 16, v56
	v_and_b32_e32 v65, 0xffff0000, v56
	v_lshlrev_b32_e32 v62, 16, v57
	v_and_b32_e32 v63, 0xffff0000, v57
	v_lshlrev_b32_e32 v60, 16, v58
	v_and_b32_e32 v61, 0xffff0000, v58
	v_lshlrev_b32_e32 v56, 16, v59
	v_and_b32_e32 v57, 0xffff0000, v59
	v_pk_mul_f32 v[58:59], v[20:21], v[88:89]
	s_nop 0
	v_pk_fma_f32 v[58:59], v[4:5], v[96:97], v[58:59]
	v_pk_mul_f32 v[96:97], v[22:23], v[86:87]
	v_pk_fma_f32 v[58:59], v[24:25], v[80:81], v[58:59]
	v_pk_fma_f32 v[94:95], v[6:7], v[94:95], v[96:97]
	v_pk_mul_f32 v[96:97], v[12:13], v[84:85]
	v_pk_fma_f32 v[58:59], v[36:37], v[72:73], v[58:59]
	v_pk_fma_f32 v[92:93], v[0:1], v[92:93], v[96:97]
	v_pk_mul_f32 v[96:97], v[14:15], v[82:83]
	v_pk_fma_f32 v[58:59], v[32:33], v[64:65], v[58:59]
	v_pk_fma_f32 v[90:91], v[2:3], v[90:91], v[96:97]
	v_mul_f32_e32 v96, 0xbfb8aa3b, v58
	v_exp_f32_e32 v98, v96
	v_mul_f32_e32 v96, 0xbfb8aa3b, v59
	v_exp_f32_e32 v99, v96
	v_pk_fma_f32 v[94:95], v[26:27], v[78:79], v[94:95]
	v_pk_fma_f32 v[92:93], v[16:17], v[76:77], v[92:93]
	v_pk_fma_f32 v[90:91], v[18:19], v[74:75], v[90:91]
	v_pk_fma_f32 v[94:95], v[38:39], v[70:71], v[94:95]
	v_pk_fma_f32 v[92:93], v[28:29], v[68:69], v[92:93]
	v_pk_fma_f32 v[90:91], v[30:31], v[66:67], v[90:91]
	v_pk_fma_f32 v[94:95], v[34:35], v[62:63], v[94:95]
	v_pk_fma_f32 v[92:93], v[8:9], v[60:61], v[92:93]
	v_pk_fma_f32 v[96:97], v[10:11], v[56:57], v[90:91]
	v_add_f32_e32 v90, 1.0, v98
	v_add_f32_e32 v91, 1.0, v99
	v_mul_f32_e32 v98, 0xbfb8aa3b, v94
	v_mul_f32_e32 v99, 0xbfb8aa3b, v95
	v_mul_f32_e32 v102, 0xbfb8aa3b, v92
	v_mul_f32_e32 v103, 0xbfb8aa3b, v93
	v_mul_f32_e32 v104, 0xbfb8aa3b, v96
	v_mul_f32_e32 v105, 0xbfb8aa3b, v97
	v_exp_f32_e32 v98, v98
	v_exp_f32_e32 v99, v99
	v_exp_f32_e32 v102, v102
	v_exp_f32_e32 v103, v103
	v_exp_f32_e32 v104, v104
	v_exp_f32_e32 v105, v105
	v_add_f32_e32 v98, 1.0, v98
	v_add_f32_e32 v99, 1.0, v99
	v_add_f32_e32 v102, 1.0, v102
	v_add_f32_e32 v103, 1.0, v103
	v_add_f32_e32 v104, 1.0, v104
	v_add_f32_e32 v105, 1.0, v105
	v_rcp_f32_e32 v90, v90
	v_rcp_f32_e32 v91, v91
	v_rcp_f32_e32 v98, v98
	v_rcp_f32_e32 v99, v99
	v_rcp_f32_e32 v102, v102
	v_rcp_f32_e32 v103, v103
	v_rcp_f32_e32 v104, v104
	v_rcp_f32_e32 v105, v105
	v_pk_mul_f32 v[58:59], v[58:59], v[90:91]
	v_pk_mul_f32 v[90:91], v[94:95], v[98:99]
	v_pk_mul_f32 v[92:93], v[92:93], v[102:103]
	v_pk_mul_f32 v[94:95], v[96:97], v[104:105]
	s_and_saveexec_b64 s[24:25], vcc
	s_cbranch_execz .LBB0_335
	v_pk_mul_f32 v[96:97], v[58:59], v[58:59]
	v_pk_mul_f32 v[98:99], v[90:91], v[90:91]
	v_add_f32_e32 v96, v96, v97
	v_add_f32_e32 v96, v98, v96
	v_pk_mul_f32 v[102:103], v[92:93], v[92:93]
	v_add_f32_e32 v96, v99, v96
	v_and_b32_e32 v98, 64, v158
	v_add_f32_e32 v96, v102, v96
	v_xor_b32_e32 v97, 1, v158
	v_add_u32_e32 v98, 64, v98
	v_pk_mul_f32 v[104:105], v[94:95], v[94:95]
	v_add_f32_e32 v96, v103, v96
	v_cmp_lt_i32_e64 s[4:5], v97, v98
	v_add_f32_e32 v96, v104, v96
	v_add_f32_e32 v96, v105, v96
	v_cndmask_b32_e64 v97, v158, v97, s[4:5]
	v_lshlrev_b32_e32 v97, 2, v97
	s_nop 1
	v_mov_b32_dpp v97, v96 quad_perm:[1,0,3,2] row_mask:0xf bank_mask:0xf
	v_add_f32_e32 v96, v96, v97
	v_xor_b32_e32 v97, 2, v158
	v_cmp_lt_i32_e64 s[4:5], v97, v98
	s_nop 1
	v_cndmask_b32_e64 v97, v158, v97, s[4:5]
	v_lshlrev_b32_e32 v97, 2, v97
	s_nop 1
	v_mov_b32_dpp v97, v96 quad_perm:[2,3,0,1] row_mask:0xf bank_mask:0xf
	v_add_f32_e32 v96, v96, v97
	v_xor_b32_e32 v97, 4, v158
	v_cmp_lt_i32_e64 s[4:5], v97, v98
	s_nop 1
	v_cndmask_b32_e64 v97, v158, v97, s[4:5]
	v_lshlrev_b32_e32 v97, 2, v97
	s_nop 1
	v_mov_b32_dpp v97, v96 row_half_mirror row_mask:0xf bank_mask:0xf
	v_add_f32_e32 v96, v96, v97
	v_xor_b32_e32 v97, 8, v158
	v_cmp_lt_i32_e64 s[4:5], v97, v98
	s_nop 1
	v_cndmask_b32_e64 v97, v158, v97, s[4:5]
	v_lshlrev_b32_e32 v97, 2, v97
	s_nop 1
	v_mov_b32_dpp v97, v96 row_ror:8 row_mask:0xf bank_mask:0xf
	v_add_f32_e32 v96, v96, v97
	v_add_f32_e32 v96, 0x358637bd, v96
	v_mul_f32_e32 v97, 0x4b800000, v96
	v_cmp_gt_f32_e64 s[4:5], s46, v96
	s_nop 1
	v_cndmask_b32_e64 v96, v96, v97, s[4:5]
	v_rsq_f32_e32 v96, v96
	s_nop 0
	v_mul_f32_e32 v97, 0x45800000, v96
	v_cndmask_b32_e64 v96, v96, v97, s[4:5]
	v_mul_f32_e32 v96, v157, v96
	v_pk_mul_f32 v[94:95], v[94:95], v[96:97] op_sel_hi:[1,0]
	v_pk_mul_f32 v[92:93], v[92:93], v[96:97] op_sel_hi:[1,0]
	v_pk_mul_f32 v[90:91], v[90:91], v[96:97] op_sel_hi:[1,0]
	v_pk_mul_f32 v[58:59], v[58:59], v[96:97] op_sel_hi:[1,0]
; DI unsigned pk2(float a, float b) { f32x2 v = {a, b}; bf16x2_t r = __builtin_convertvector(v, bf16x2_t); return __builtin_bit_cast(unsigned, r); }
; DI float bflo(unsigned u) { return __uint_as_float(u << 16); }
; DI float bfhi(unsigned u) { return __uint_as_float(u & 0xffff0000u); }
; DI float siluf_(float x) { return x * __builtin_amdgcn_rcpf(1.f + __expf(-x)); }
; DI void dn_conv_phase(const Params& p) {
;     ...
;         for (int tt = 0; tt < SEG; ++tt) {
;             { const u32x4 u = rows[tt + 4]; const int sl = (tt + 4) % 5;
;               ring[sl][0] = (f32x2){bflo(u.x), bfhi(u.x)}; ring[sl][1] = (f32x2){bflo(u.y), bfhi(u.y)}; ring[sl][2] = (f32x2){bflo(u.z), bfhi(u.z)}; ring[sl][3] = (f32x2){bflo(u.w), bfhi(u.w)}; }
;             f32x2 o2[4];
; #pragma unroll
;             for (int e = 0; e < 4; ++e) o2[e] = w[0][e] * ring[tt % 5][e];
; #pragma unroll
;             for (int j = 1; j < 5; ++j)
; #pragma unroll
;                 for (int e = 0; e < 4; ++e) o2[e] += w[j][e] * ring[(tt + j) % 5][e];
;             float o[8];
; #pragma unroll
;             for (int e = 0; e < 4; ++e) { o[2 * e] = siluf_(o2[e].x); o[2 * e + 1] = siluf_(o2[e].y); }
;             if (part < 2) {
;                 float ss = 0.f;
; #pragma unroll
;                 for (int e = 0; e < 8; ++e) ss += o[e] * o[e];
;                 ss += __shfl_xor(ss, 1); ss += __shfl_xor(ss, 2); ss += __shfl_xor(ss, 4); ss += __shfl_xor(ss, 8);
;                 const float sc = rsqrtf(ss + EPS) * (part == 0 ? 0.08838834764831845f : 1.f);
; #pragma unroll
;                 for (int e = 0; e < 8; ++e) o[e] *= sc;
;             }
;             u32x4 ov; ov.x = pk2(o[0], o[1]); ov.y = pk2(o[2], o[3]); ov.z = pk2(o[4], o[5]); ov.w = pk2(o[6], o[7]);
;             *(u32x4*)(QKV + (size_t)(row0 + tt) * 1536 + ch) = ov;
.LBB0_335:
	s_or_b64 exec, exec, s[24:25]
	v_cvt_pk_bf16_f32 v96, v58, v59
	v_or_b32_e32 v58, 11, v156
	v_cvt_pk_bf16_f32 v97, v90, v91
	v_cvt_pk_bf16_f32 v98, v92, v93
	v_cvt_pk_bf16_f32 v99, v94, v95
	v_mad_i64_i32 v[58:59], s[4:5], v58, s45, v[100:101]
	global_store_dwordx4 v[58:59], v[96:99], off
	v_lshlrev_b32_e32 v92, 16, v52
	v_and_b32_e32 v93, 0xffff0000, v52
	v_lshlrev_b32_e32 v90, 16, v53
	v_and_b32_e32 v91, 0xffff0000, v53
	v_lshlrev_b32_e32 v58, 16, v54
	v_and_b32_e32 v59, 0xffff0000, v54
	v_lshlrev_b32_e32 v52, 16, v55
	v_and_b32_e32 v53, 0xffff0000, v55
	v_pk_mul_f32 v[54:55], v[20:21], v[80:81]
	s_nop 0
	v_pk_fma_f32 v[54:55], v[4:5], v[88:89], v[54:55]
	v_pk_mul_f32 v[88:89], v[22:23], v[78:79]
	v_pk_fma_f32 v[54:55], v[24:25], v[72:73], v[54:55]
	v_pk_fma_f32 v[86:87], v[6:7], v[86:87], v[88:89]
	v_pk_mul_f32 v[88:89], v[12:13], v[76:77]
	v_pk_fma_f32 v[54:55], v[36:37], v[64:65], v[54:55]
	v_pk_fma_f32 v[84:85], v[0:1], v[84:85], v[88:89]
	v_pk_mul_f32 v[88:89], v[14:15], v[74:75]
	v_pk_fma_f32 v[54:55], v[32:33], v[92:93], v[54:55]
	v_pk_fma_f32 v[82:83], v[2:3], v[82:83], v[88:89]
	v_mul_f32_e32 v88, 0xbfb8aa3b, v54
	v_exp_f32_e32 v94, v88
	v_mul_f32_e32 v88, 0xbfb8aa3b, v55
	v_exp_f32_e32 v95, v88
	v_pk_fma_f32 v[86:87], v[26:27], v[70:71], v[86:87]
	v_pk_fma_f32 v[84:85], v[16:17], v[68:69], v[84:85]
	v_pk_fma_f32 v[82:83], v[18:19], v[66:67], v[82:83]
	v_pk_fma_f32 v[86:87], v[38:39], v[62:63], v[86:87]
	v_pk_fma_f32 v[84:85], v[28:29], v[60:61], v[84:85]
	v_pk_fma_f32 v[82:83], v[30:31], v[56:57], v[82:83]
	v_pk_fma_f32 v[86:87], v[34:35], v[90:91], v[86:87]
	v_pk_fma_f32 v[84:85], v[8:9], v[58:59], v[84:85]
	v_pk_fma_f32 v[88:89], v[10:11], v[52:53], v[82:83]
	v_add_f32_e32 v82, 1.0, v94
	v_add_f32_e32 v83, 1.0, v95
	v_mul_f32_e32 v94, 0xbfb8aa3b, v86
	v_mul_f32_e32 v95, 0xbfb8aa3b, v87
	v_mul_f32_e32 v96, 0xbfb8aa3b, v84
	v_mul_f32_e32 v97, 0xbfb8aa3b, v85
	v_mul_f32_e32 v98, 0xbfb8aa3b, v88
	v_mul_f32_e32 v99, 0xbfb8aa3b, v89
	v_exp_f32_e32 v94, v94
	v_exp_f32_e32 v95, v95
	v_exp_f32_e32 v96, v96
	v_exp_f32_e32 v97, v97
	v_exp_f32_e32 v98, v98
	v_exp_f32_e32 v99, v99
	v_add_f32_e32 v94, 1.0, v94
	v_add_f32_e32 v95, 1.0, v95
	v_add_f32_e32 v96, 1.0, v96
	v_add_f32_e32 v97, 1.0, v97
	v_add_f32_e32 v98, 1.0, v98
	v_add_f32_e32 v99, 1.0, v99
	v_rcp_f32_e32 v82, v82
	v_rcp_f32_e32 v83, v83
	v_rcp_f32_e32 v94, v94
	v_rcp_f32_e32 v95, v95
	v_rcp_f32_e32 v96, v96
	v_rcp_f32_e32 v97, v97
	v_rcp_f32_e32 v98, v98
	v_rcp_f32_e32 v99, v99
	v_pk_mul_f32 v[54:55], v[54:55], v[82:83]
	v_pk_mul_f32 v[82:83], v[86:87], v[94:95]
	v_pk_mul_f32 v[84:85], v[84:85], v[96:97]
	v_pk_mul_f32 v[86:87], v[88:89], v[98:99]
	s_and_saveexec_b64 s[24:25], vcc
	s_cbranch_execz .LBB0_337
	v_pk_mul_f32 v[88:89], v[54:55], v[54:55]
	v_pk_mul_f32 v[94:95], v[82:83], v[82:83]
	v_add_f32_e32 v88, v88, v89
	v_add_f32_e32 v88, v94, v88
	v_pk_mul_f32 v[96:97], v[84:85], v[84:85]
	v_add_f32_e32 v88, v95, v88
	v_and_b32_e32 v94, 64, v158
	v_add_f32_e32 v88, v96, v88
	v_xor_b32_e32 v89, 1, v158
	v_add_u32_e32 v94, 64, v94
	v_pk_mul_f32 v[98:99], v[86:87], v[86:87]
	v_add_f32_e32 v88, v97, v88
	v_cmp_lt_i32_e64 s[4:5], v89, v94
	v_add_f32_e32 v88, v98, v88
	v_add_f32_e32 v88, v99, v88
	v_cndmask_b32_e64 v89, v158, v89, s[4:5]
	v_lshlrev_b32_e32 v89, 2, v89
	s_nop 1
	v_mov_b32_dpp v89, v88 quad_perm:[1,0,3,2] row_mask:0xf bank_mask:0xf
	v_add_f32_e32 v88, v88, v89
	v_xor_b32_e32 v89, 2, v158
	v_cmp_lt_i32_e64 s[4:5], v89, v94
	s_nop 1
	v_cndmask_b32_e64 v89, v158, v89, s[4:5]
	v_lshlrev_b32_e32 v89, 2, v89
	s_nop 1
	v_mov_b32_dpp v89, v88 quad_perm:[2,3,0,1] row_mask:0xf bank_mask:0xf
	v_add_f32_e32 v88, v88, v89
	v_xor_b32_e32 v89, 4, v158
	v_cmp_lt_i32_e64 s[4:5], v89, v94
	s_nop 1
	v_cndmask_b32_e64 v89, v158, v89, s[4:5]
	v_lshlrev_b32_e32 v89, 2, v89
	s_nop 1
	v_mov_b32_dpp v89, v88 row_half_mirror row_mask:0xf bank_mask:0xf
	v_add_f32_e32 v88, v88, v89
	v_xor_b32_e32 v89, 8, v158
	v_cmp_lt_i32_e64 s[4:5], v89, v94
	s_nop 1
	v_cndmask_b32_e64 v89, v158, v89, s[4:5]
	v_lshlrev_b32_e32 v89, 2, v89
	s_nop 1
	v_mov_b32_dpp v89, v88 row_ror:8 row_mask:0xf bank_mask:0xf
	v_add_f32_e32 v88, v88, v89
	v_add_f32_e32 v88, 0x358637bd, v88
	v_mul_f32_e32 v89, 0x4b800000, v88
	v_cmp_gt_f32_e64 s[4:5], s46, v88
	s_nop 1
	v_cndmask_b32_e64 v88, v88, v89, s[4:5]
	v_rsq_f32_e32 v88, v88
	s_nop 0
	v_mul_f32_e32 v89, 0x45800000, v88
	v_cndmask_b32_e64 v88, v88, v89, s[4:5]
	v_mul_f32_e32 v88, v157, v88
	v_pk_mul_f32 v[86:87], v[86:87], v[88:89] op_sel_hi:[1,0]
	v_pk_mul_f32 v[84:85], v[84:85], v[88:89] op_sel_hi:[1,0]
	v_pk_mul_f32 v[82:83], v[82:83], v[88:89] op_sel_hi:[1,0]
	v_pk_mul_f32 v[54:55], v[54:55], v[88:89] op_sel_hi:[1,0]
; DI unsigned pk2(float a, float b) { f32x2 v = {a, b}; bf16x2_t r = __builtin_convertvector(v, bf16x2_t); return __builtin_bit_cast(unsigned, r); }
; DI float bflo(unsigned u) { return __uint_as_float(u << 16); }
; DI float bfhi(unsigned u) { return __uint_as_float(u & 0xffff0000u); }
; DI float siluf_(float x) { return x * __builtin_amdgcn_rcpf(1.f + __expf(-x)); }
; DI void dn_conv_phase(const Params& p) {
;     ...
;         for (int tt = 0; tt < SEG; ++tt) {
;             { const u32x4 u = rows[tt + 4]; const int sl = (tt + 4) % 5;
;               ring[sl][0] = (f32x2){bflo(u.x), bfhi(u.x)}; ring[sl][1] = (f32x2){bflo(u.y), bfhi(u.y)}; ring[sl][2] = (f32x2){bflo(u.z), bfhi(u.z)}; ring[sl][3] = (f32x2){bflo(u.w), bfhi(u.w)}; }
;             f32x2 o2[4];
; #pragma unroll
;             for (int e = 0; e < 4; ++e) o2[e] = w[0][e] * ring[tt % 5][e];
; #pragma unroll
;             for (int j = 1; j < 5; ++j)
; #pragma unroll
;                 for (int e = 0; e < 4; ++e) o2[e] += w[j][e] * ring[(tt + j) % 5][e];
;             float o[8];
; #pragma unroll
;             for (int e = 0; e < 4; ++e) { o[2 * e] = siluf_(o2[e].x); o[2 * e + 1] = siluf_(o2[e].y); }
;             if (part < 2) {
;                 float ss = 0.f;
; #pragma unroll
;                 for (int e = 0; e < 8; ++e) ss += o[e] * o[e];
;                 ss += __shfl_xor(ss, 1); ss += __shfl_xor(ss, 2); ss += __shfl_xor(ss, 4); ss += __shfl_xor(ss, 8);
;                 const float sc = rsqrtf(ss + EPS) * (part == 0 ? 0.08838834764831845f : 1.f);
; #pragma unroll
;                 for (int e = 0; e < 8; ++e) o[e] *= sc;
;             }
;             u32x4 ov; ov.x = pk2(o[0], o[1]); ov.y = pk2(o[2], o[3]); ov.z = pk2(o[4], o[5]); ov.w = pk2(o[6], o[7]);
;             *(u32x4*)(QKV + (size_t)(row0 + tt) * 1536 + ch) = ov;
.LBB0_337:
	s_or_b64 exec, exec, s[24:25]
	v_cvt_pk_bf16_f32 v96, v84, v85
	v_pk_mul_f32 v[84:85], v[20:21], v[72:73]
	v_cvt_pk_bf16_f32 v94, v54, v55
	v_pk_fma_f32 v[80:81], v[4:5], v[80:81], v[84:85]
	v_pk_mul_f32 v[84:85], v[22:23], v[70:71]
	v_or_b32_e32 v54, 12, v156
	v_pk_fma_f32 v[78:79], v[6:7], v[78:79], v[84:85]
	v_pk_mul_f32 v[84:85], v[12:13], v[68:69]
	v_cvt_pk_bf16_f32 v95, v82, v83
	v_cvt_pk_bf16_f32 v97, v86, v87
	v_mad_i64_i32 v[54:55], s[4:5], v54, s45, v[100:101]
	v_pk_fma_f32 v[76:77], v[0:1], v[76:77], v[84:85]
	v_pk_fma_f32 v[80:81], v[24:25], v[64:65], v[80:81]
	global_store_dwordx4 v[54:55], v[94:97], off
	v_lshlrev_b32_e32 v54, 16, v48
	v_and_b32_e32 v55, 0xffff0000, v48
	v_pk_fma_f32 v[76:77], v[16:17], v[60:61], v[76:77]
	v_pk_fma_f32 v[80:81], v[36:37], v[92:93], v[80:81]
	v_lshlrev_b32_e32 v82, 16, v50
	v_and_b32_e32 v83, 0xffff0000, v50
	v_pk_mul_f32 v[84:85], v[14:15], v[66:67]
	v_pk_fma_f32 v[76:77], v[28:29], v[58:59], v[76:77]
	v_pk_fma_f32 v[80:81], v[32:33], v[54:55], v[80:81]
	v_pk_fma_f32 v[74:75], v[2:3], v[74:75], v[84:85]
	v_pk_fma_f32 v[84:85], v[8:9], v[82:83], v[76:77]
	v_mul_f32_e32 v76, 0xbfb8aa3b, v80
	v_mul_f32_e32 v77, 0xbfb8aa3b, v81
	v_exp_f32_e32 v76, v76
	v_exp_f32_e32 v77, v77
	v_pk_fma_f32 v[78:79], v[26:27], v[62:63], v[78:79]
	v_pk_fma_f32 v[74:75], v[18:19], v[56:57], v[74:75]
	v_lshlrev_b32_e32 v48, 16, v49
	v_and_b32_e32 v49, 0xffff0000, v49
	v_lshlrev_b32_e32 v50, 16, v51
	v_and_b32_e32 v51, 0xffff0000, v51
	v_pk_fma_f32 v[78:79], v[38:39], v[90:91], v[78:79]
	v_pk_fma_f32 v[74:75], v[30:31], v[52:53], v[74:75]
	v_pk_fma_f32 v[78:79], v[34:35], v[48:49], v[78:79]
	v_pk_fma_f32 v[86:87], v[10:11], v[50:51], v[74:75]
	v_add_f32_e32 v74, 1.0, v76
	v_add_f32_e32 v75, 1.0, v77
	v_mul_f32_e32 v76, 0xbfb8aa3b, v78
	v_mul_f32_e32 v77, 0xbfb8aa3b, v79
	v_mul_f32_e32 v88, 0xbfb8aa3b, v84
	v_mul_f32_e32 v89, 0xbfb8aa3b, v85
	v_mul_f32_e32 v94, 0xbfb8aa3b, v86
	v_mul_f32_e32 v95, 0xbfb8aa3b, v87
	v_exp_f32_e32 v76, v76
	v_exp_f32_e32 v77, v77
	v_exp_f32_e32 v88, v88
	v_exp_f32_e32 v89, v89
	v_exp_f32_e32 v94, v94
	v_exp_f32_e32 v95, v95
	v_add_f32_e32 v76, 1.0, v76
	v_add_f32_e32 v77, 1.0, v77
	v_add_f32_e32 v88, 1.0, v88
	v_add_f32_e32 v89, 1.0, v89
	v_add_f32_e32 v94, 1.0, v94
	v_add_f32_e32 v95, 1.0, v95
	v_rcp_f32_e32 v74, v74
	v_rcp_f32_e32 v75, v75
	v_rcp_f32_e32 v76, v76
	v_rcp_f32_e32 v77, v77
	v_rcp_f32_e32 v88, v88
	v_rcp_f32_e32 v89, v89
	v_rcp_f32_e32 v94, v94
	v_rcp_f32_e32 v95, v95
	v_pk_mul_f32 v[74:75], v[80:81], v[74:75]
	v_pk_mul_f32 v[76:77], v[78:79], v[76:77]
	v_pk_mul_f32 v[78:79], v[84:85], v[88:89]
	v_pk_mul_f32 v[80:81], v[86:87], v[94:95]
	s_and_saveexec_b64 s[24:25], vcc
	s_cbranch_execz .LBB0_339
	v_pk_mul_f32 v[84:85], v[74:75], v[74:75]
	v_pk_mul_f32 v[86:87], v[76:77], v[76:77]
	v_add_f32_e32 v84, v84, v85
	v_add_f32_e32 v84, v86, v84
	v_pk_mul_f32 v[88:89], v[78:79], v[78:79]
	v_add_f32_e32 v84, v87, v84
	v_and_b32_e32 v86, 64, v158
	v_add_f32_e32 v84, v88, v84
	v_xor_b32_e32 v85, 1, v158
	v_add_u32_e32 v86, 64, v86
	v_pk_mul_f32 v[94:95], v[80:81], v[80:81]
	v_add_f32_e32 v84, v89, v84
	v_cmp_lt_i32_e64 s[4:5], v85, v86
	v_add_f32_e32 v84, v94, v84
	v_add_f32_e32 v84, v95, v84
	v_cndmask_b32_e64 v85, v158, v85, s[4:5]
	v_lshlrev_b32_e32 v85, 2, v85
	s_nop 1
	v_mov_b32_dpp v85, v84 quad_perm:[1,0,3,2] row_mask:0xf bank_mask:0xf
	v_add_f32_e32 v84, v84, v85
	v_xor_b32_e32 v85, 2, v158
	v_cmp_lt_i32_e64 s[4:5], v85, v86
	s_nop 1
	v_cndmask_b32_e64 v85, v158, v85, s[4:5]
	v_lshlrev_b32_e32 v85, 2, v85
	s_nop 1
	v_mov_b32_dpp v85, v84 quad_perm:[2,3,0,1] row_mask:0xf bank_mask:0xf
	v_add_f32_e32 v84, v84, v85
	v_xor_b32_e32 v85, 4, v158
	v_cmp_lt_i32_e64 s[4:5], v85, v86
	s_nop 1
	v_cndmask_b32_e64 v85, v158, v85, s[4:5]
	v_lshlrev_b32_e32 v85, 2, v85
	s_nop 1
	v_mov_b32_dpp v85, v84 row_half_mirror row_mask:0xf bank_mask:0xf
	v_add_f32_e32 v84, v84, v85
	v_xor_b32_e32 v85, 8, v158
	v_cmp_lt_i32_e64 s[4:5], v85, v86
	s_nop 1
	v_cndmask_b32_e64 v85, v158, v85, s[4:5]
	v_lshlrev_b32_e32 v85, 2, v85
	s_nop 1
	v_mov_b32_dpp v85, v84 row_ror:8 row_mask:0xf bank_mask:0xf
	v_add_f32_e32 v84, v84, v85
	v_add_f32_e32 v84, 0x358637bd, v84
	v_mul_f32_e32 v85, 0x4b800000, v84
	v_cmp_gt_f32_e64 s[4:5], s46, v84
	s_nop 1
	v_cndmask_b32_e64 v84, v84, v85, s[4:5]
	v_rsq_f32_e32 v84, v84
	s_nop 0
	v_mul_f32_e32 v85, 0x45800000, v84
	v_cndmask_b32_e64 v84, v84, v85, s[4:5]
	v_mul_f32_e32 v84, v157, v84
	v_pk_mul_f32 v[80:81], v[80:81], v[84:85] op_sel_hi:[1,0]
	v_pk_mul_f32 v[78:79], v[78:79], v[84:85] op_sel_hi:[1,0]
	v_pk_mul_f32 v[76:77], v[76:77], v[84:85] op_sel_hi:[1,0]
	v_pk_mul_f32 v[74:75], v[74:75], v[84:85] op_sel_hi:[1,0]
; DI unsigned pk2(float a, float b) { f32x2 v = {a, b}; bf16x2_t r = __builtin_convertvector(v, bf16x2_t); return __builtin_bit_cast(unsigned, r); }
; DI float bflo(unsigned u) { return __uint_as_float(u << 16); }
; DI float bfhi(unsigned u) { return __uint_as_float(u & 0xffff0000u); }
; DI float siluf_(float x) { return x * __builtin_amdgcn_rcpf(1.f + __expf(-x)); }
; DI void dn_conv_phase(const Params& p) {
;     ...
;         for (int tt = 0; tt < SEG; ++tt) {
;             { const u32x4 u = rows[tt + 4]; const int sl = (tt + 4) % 5;
;               ring[sl][0] = (f32x2){bflo(u.x), bfhi(u.x)}; ring[sl][1] = (f32x2){bflo(u.y), bfhi(u.y)}; ring[sl][2] = (f32x2){bflo(u.z), bfhi(u.z)}; ring[sl][3] = (f32x2){bflo(u.w), bfhi(u.w)}; }
;             f32x2 o2[4];
; #pragma unroll
;             for (int e = 0; e < 4; ++e) o2[e] = w[0][e] * ring[tt % 5][e];
; #pragma unroll
;             for (int j = 1; j < 5; ++j)
; #pragma unroll
;                 for (int e = 0; e < 4; ++e) o2[e] += w[j][e] * ring[(tt + j) % 5][e];
;             float o[8];
; #pragma unroll
;             for (int e = 0; e < 4; ++e) { o[2 * e] = siluf_(o2[e].x); o[2 * e + 1] = siluf_(o2[e].y); }
;             if (part < 2) {
;                 float ss = 0.f;
; #pragma unroll
;                 for (int e = 0; e < 8; ++e) ss += o[e] * o[e];
;                 ss += __shfl_xor(ss, 1); ss += __shfl_xor(ss, 2); ss += __shfl_xor(ss, 4); ss += __shfl_xor(ss, 8);
;                 const float sc = rsqrtf(ss + EPS) * (part == 0 ? 0.08838834764831845f : 1.f);
; #pragma unroll
;                 for (int e = 0; e < 8; ++e) o[e] *= sc;
;             }
;             u32x4 ov; ov.x = pk2(o[0], o[1]); ov.y = pk2(o[2], o[3]); ov.z = pk2(o[4], o[5]); ov.w = pk2(o[6], o[7]);
;             *(u32x4*)(QKV + (size_t)(row0 + tt) * 1536 + ch) = ov;
.LBB0_339:
	s_or_b64 exec, exec, s[24:25]
	v_cvt_pk_bf16_f32 v74, v74, v75
	v_cvt_pk_bf16_f32 v75, v76, v77
	v_cvt_pk_bf16_f32 v76, v78, v79
	v_or_b32_e32 v78, 13, v156
	v_cvt_pk_bf16_f32 v77, v80, v81
	v_mad_i64_i32 v[78:79], s[4:5], v78, s45, v[100:101]
	global_store_dwordx4 v[78:79], v[74:77], off
	v_pk_mul_f32 v[78:79], v[20:21], v[64:65]
	s_nop 0
	v_pk_fma_f32 v[72:73], v[4:5], v[72:73], v[78:79]
	v_pk_mul_f32 v[78:79], v[22:23], v[62:63]
	v_pk_fma_f32 v[72:73], v[24:25], v[92:93], v[72:73]
	v_pk_fma_f32 v[70:71], v[6:7], v[70:71], v[78:79]
	v_pk_mul_f32 v[78:79], v[12:13], v[60:61]
	v_lshlrev_b32_e32 v74, 16, v44
	v_pk_fma_f32 v[68:69], v[0:1], v[68:69], v[78:79]
	v_and_b32_e32 v75, 0xffff0000, v44
	v_pk_fma_f32 v[68:69], v[16:17], v[58:59], v[68:69]
	v_pk_fma_f32 v[72:73], v[36:37], v[54:55], v[72:73]
	v_lshlrev_b32_e32 v76, 16, v46
	v_and_b32_e32 v77, 0xffff0000, v46
	v_pk_mul_f32 v[78:79], v[14:15], v[56:57]
	v_pk_fma_f32 v[68:69], v[28:29], v[82:83], v[68:69]
	v_pk_fma_f32 v[72:73], v[32:33], v[74:75], v[72:73]
	v_pk_fma_f32 v[66:67], v[2:3], v[66:67], v[78:79]
	v_pk_fma_f32 v[78:79], v[8:9], v[76:77], v[68:69]
	v_mul_f32_e32 v68, 0xbfb8aa3b, v72
	v_mul_f32_e32 v69, 0xbfb8aa3b, v73
	v_exp_f32_e32 v68, v68
	v_exp_f32_e32 v69, v69
	v_pk_fma_f32 v[70:71], v[26:27], v[90:91], v[70:71]
	v_pk_fma_f32 v[66:67], v[18:19], v[52:53], v[66:67]
	v_lshlrev_b32_e32 v44, 16, v45
	v_and_b32_e32 v45, 0xffff0000, v45
	v_lshlrev_b32_e32 v46, 16, v47
	v_and_b32_e32 v47, 0xffff0000, v47
	v_pk_fma_f32 v[70:71], v[38:39], v[48:49], v[70:71]
	v_pk_fma_f32 v[66:67], v[30:31], v[50:51], v[66:67]
	v_pk_fma_f32 v[70:71], v[34:35], v[44:45], v[70:71]
	v_pk_fma_f32 v[80:81], v[10:11], v[46:47], v[66:67]
	v_add_f32_e32 v66, 1.0, v68
	v_add_f32_e32 v67, 1.0, v69
	v_mul_f32_e32 v68, 0xbfb8aa3b, v70
	v_mul_f32_e32 v69, 0xbfb8aa3b, v71
	v_mul_f32_e32 v84, 0xbfb8aa3b, v78
	v_mul_f32_e32 v85, 0xbfb8aa3b, v79
	v_mul_f32_e32 v86, 0xbfb8aa3b, v80
	v_mul_f32_e32 v87, 0xbfb8aa3b, v81
	v_exp_f32_e32 v68, v68
	v_exp_f32_e32 v69, v69
	v_exp_f32_e32 v84, v84
	v_exp_f32_e32 v85, v85
	v_exp_f32_e32 v86, v86
	v_exp_f32_e32 v87, v87
	v_add_f32_e32 v68, 1.0, v68
	v_add_f32_e32 v69, 1.0, v69
	v_add_f32_e32 v84, 1.0, v84
	v_add_f32_e32 v85, 1.0, v85
	v_add_f32_e32 v86, 1.0, v86
	v_add_f32_e32 v87, 1.0, v87
	v_rcp_f32_e32 v66, v66
	v_rcp_f32_e32 v67, v67
	v_rcp_f32_e32 v68, v68
	v_rcp_f32_e32 v69, v69
	v_rcp_f32_e32 v84, v84
	v_rcp_f32_e32 v85, v85
	v_rcp_f32_e32 v86, v86
	v_rcp_f32_e32 v87, v87
	v_pk_mul_f32 v[66:67], v[72:73], v[66:67]
	v_pk_mul_f32 v[68:69], v[70:71], v[68:69]
	v_pk_mul_f32 v[70:71], v[78:79], v[84:85]
	v_pk_mul_f32 v[72:73], v[80:81], v[86:87]
	s_and_saveexec_b64 s[24:25], vcc
	s_cbranch_execz .LBB0_341
	v_pk_mul_f32 v[78:79], v[66:67], v[66:67]
	v_pk_mul_f32 v[80:81], v[68:69], v[68:69]
	v_add_f32_e32 v78, v78, v79
	v_add_f32_e32 v78, v80, v78
	v_pk_mul_f32 v[84:85], v[70:71], v[70:71]
	v_add_f32_e32 v78, v81, v78
	v_and_b32_e32 v80, 64, v158
	v_add_f32_e32 v78, v84, v78
	v_xor_b32_e32 v79, 1, v158
	v_add_u32_e32 v80, 64, v80
	v_pk_mul_f32 v[86:87], v[72:73], v[72:73]
	v_add_f32_e32 v78, v85, v78
	v_cmp_lt_i32_e64 s[4:5], v79, v80
	v_add_f32_e32 v78, v86, v78
	v_add_f32_e32 v78, v87, v78
	v_cndmask_b32_e64 v79, v158, v79, s[4:5]
	v_lshlrev_b32_e32 v79, 2, v79
	s_nop 1
	v_mov_b32_dpp v79, v78 quad_perm:[1,0,3,2] row_mask:0xf bank_mask:0xf
	v_add_f32_e32 v78, v78, v79
	v_xor_b32_e32 v79, 2, v158
	v_cmp_lt_i32_e64 s[4:5], v79, v80
	s_nop 1
	v_cndmask_b32_e64 v79, v158, v79, s[4:5]
	v_lshlrev_b32_e32 v79, 2, v79
	s_nop 1
	v_mov_b32_dpp v79, v78 quad_perm:[2,3,0,1] row_mask:0xf bank_mask:0xf
	v_add_f32_e32 v78, v78, v79
	v_xor_b32_e32 v79, 4, v158
	v_cmp_lt_i32_e64 s[4:5], v79, v80
	s_nop 1
	v_cndmask_b32_e64 v79, v158, v79, s[4:5]
	v_lshlrev_b32_e32 v79, 2, v79
	s_nop 1
	v_mov_b32_dpp v79, v78 row_half_mirror row_mask:0xf bank_mask:0xf
	v_add_f32_e32 v78, v78, v79
	v_xor_b32_e32 v79, 8, v158
	v_cmp_lt_i32_e64 s[4:5], v79, v80
	s_nop 1
	v_cndmask_b32_e64 v79, v158, v79, s[4:5]
	v_lshlrev_b32_e32 v79, 2, v79
	s_nop 1
	v_mov_b32_dpp v79, v78 row_ror:8 row_mask:0xf bank_mask:0xf
	v_add_f32_e32 v78, v78, v79
	v_add_f32_e32 v78, 0x358637bd, v78
	v_mul_f32_e32 v79, 0x4b800000, v78
	v_cmp_gt_f32_e64 s[4:5], s46, v78
	s_nop 1
	v_cndmask_b32_e64 v78, v78, v79, s[4:5]
	v_rsq_f32_e32 v78, v78
	s_nop 0
	v_mul_f32_e32 v79, 0x45800000, v78
	v_cndmask_b32_e64 v78, v78, v79, s[4:5]
	v_mul_f32_e32 v78, v157, v78
	v_pk_mul_f32 v[72:73], v[72:73], v[78:79] op_sel_hi:[1,0]
	v_pk_mul_f32 v[70:71], v[70:71], v[78:79] op_sel_hi:[1,0]
	v_pk_mul_f32 v[68:69], v[68:69], v[78:79] op_sel_hi:[1,0]
	v_pk_mul_f32 v[66:67], v[66:67], v[78:79] op_sel_hi:[1,0]
; DI unsigned pk2(float a, float b) { f32x2 v = {a, b}; bf16x2_t r = __builtin_convertvector(v, bf16x2_t); return __builtin_bit_cast(unsigned, r); }
; DI float bflo(unsigned u) { return __uint_as_float(u << 16); }
; DI float bfhi(unsigned u) { return __uint_as_float(u & 0xffff0000u); }
; DI float siluf_(float x) { return x * __builtin_amdgcn_rcpf(1.f + __expf(-x)); }
; DI void dn_conv_phase(const Params& p) {
;     ...
;         for (int tt = 0; tt < SEG; ++tt) {
;             { const u32x4 u = rows[tt + 4]; const int sl = (tt + 4) % 5;
;               ring[sl][0] = (f32x2){bflo(u.x), bfhi(u.x)}; ring[sl][1] = (f32x2){bflo(u.y), bfhi(u.y)}; ring[sl][2] = (f32x2){bflo(u.z), bfhi(u.z)}; ring[sl][3] = (f32x2){bflo(u.w), bfhi(u.w)}; }
;             f32x2 o2[4];
; #pragma unroll
;             for (int e = 0; e < 4; ++e) o2[e] = w[0][e] * ring[tt % 5][e];
; #pragma unroll
;             for (int j = 1; j < 5; ++j)
; #pragma unroll
;                 for (int e = 0; e < 4; ++e) o2[e] += w[j][e] * ring[(tt + j) % 5][e];
;             float o[8];
; #pragma unroll
;             for (int e = 0; e < 4; ++e) { o[2 * e] = siluf_(o2[e].x); o[2 * e + 1] = siluf_(o2[e].y); }
;             if (part < 2) {
;                 float ss = 0.f;
; #pragma unroll
;                 for (int e = 0; e < 8; ++e) ss += o[e] * o[e];
;                 ss += __shfl_xor(ss, 1); ss += __shfl_xor(ss, 2); ss += __shfl_xor(ss, 4); ss += __shfl_xor(ss, 8);
;                 const float sc = rsqrtf(ss + EPS) * (part == 0 ? 0.08838834764831845f : 1.f);
; #pragma unroll
;                 for (int e = 0; e < 8; ++e) o[e] *= sc;
;             }
;             u32x4 ov; ov.x = pk2(o[0], o[1]); ov.y = pk2(o[2], o[3]); ov.z = pk2(o[4], o[5]); ov.w = pk2(o[6], o[7]);
;             *(u32x4*)(QKV + (size_t)(row0 + tt) * 1536 + ch) = ov;
.LBB0_341:
	s_or_b64 exec, exec, s[24:25]
	v_pk_mul_f32 v[20:21], v[20:21], v[92:93]
	v_pk_mul_f32 v[12:13], v[12:13], v[58:59]
	v_pk_fma_f32 v[4:5], v[4:5], v[64:65], v[20:21]
	v_pk_mul_f32 v[20:21], v[22:23], v[90:91]
	v_pk_fma_f32 v[0:1], v[0:1], v[60:61], v[12:13]
	v_pk_mul_f32 v[12:13], v[14:15], v[52:53]
	v_cvt_pk_bf16_f32 v66, v66, v67
	v_cvt_pk_bf16_f32 v67, v68, v69
	v_cvt_pk_bf16_f32 v68, v70, v71
	v_or_b32_e32 v70, 14, v156
	v_pk_fma_f32 v[6:7], v[6:7], v[62:63], v[20:21]
	v_pk_fma_f32 v[2:3], v[2:3], v[56:57], v[12:13]
	v_cvt_pk_bf16_f32 v69, v72, v73
	v_mad_i64_i32 v[70:71], s[4:5], v70, s45, v[100:101]
	v_pk_fma_f32 v[4:5], v[24:25], v[54:55], v[4:5]
	v_pk_fma_f32 v[6:7], v[26:27], v[48:49], v[6:7]
	v_pk_fma_f32 v[0:1], v[16:17], v[82:83], v[0:1]
	v_pk_fma_f32 v[2:3], v[18:19], v[50:51], v[2:3]
	global_store_dwordx4 v[70:71], v[66:69], off
	v_pk_fma_f32 v[4:5], v[36:37], v[74:75], v[4:5]
	v_pk_fma_f32 v[6:7], v[38:39], v[44:45], v[6:7]
	v_lshlrev_b32_e32 v66, 16, v40
	v_and_b32_e32 v67, 0xffff0000, v40
	v_lshlrev_b32_e32 v40, 16, v41
	v_and_b32_e32 v41, 0xffff0000, v41
	v_lshlrev_b32_e32 v68, 16, v42
	v_and_b32_e32 v69, 0xffff0000, v42
	v_lshlrev_b32_e32 v42, 16, v43
	v_and_b32_e32 v43, 0xffff0000, v43
	v_pk_fma_f32 v[0:1], v[28:29], v[76:77], v[0:1]
	v_pk_fma_f32 v[2:3], v[30:31], v[46:47], v[2:3]
	v_pk_fma_f32 v[4:5], v[32:33], v[66:67], v[4:5]
	v_pk_fma_f32 v[6:7], v[34:35], v[40:41], v[6:7]
	v_pk_fma_f32 v[8:9], v[8:9], v[68:69], v[0:1]
	v_pk_fma_f32 v[10:11], v[10:11], v[42:43], v[2:3]
	v_mul_f32_e32 v0, 0xbfb8aa3b, v4
	v_mul_f32_e32 v1, 0xbfb8aa3b, v5
	v_mul_f32_e32 v2, 0xbfb8aa3b, v6
	v_mul_f32_e32 v3, 0xbfb8aa3b, v7
	v_mul_f32_e32 v12, 0xbfb8aa3b, v8
	v_mul_f32_e32 v13, 0xbfb8aa3b, v9
	v_mul_f32_e32 v14, 0xbfb8aa3b, v10
	v_mul_f32_e32 v15, 0xbfb8aa3b, v11
	v_exp_f32_e32 v0, v0
	v_exp_f32_e32 v1, v1
	v_exp_f32_e32 v2, v2
	v_exp_f32_e32 v3, v3
	v_exp_f32_e32 v12, v12
	v_exp_f32_e32 v13, v13
	v_exp_f32_e32 v14, v14
	v_exp_f32_e32 v15, v15
	v_add_f32_e32 v0, 1.0, v0
	v_add_f32_e32 v1, 1.0, v1
	v_add_f32_e32 v2, 1.0, v2
	v_add_f32_e32 v3, 1.0, v3
	v_add_f32_e32 v12, 1.0, v12
	v_add_f32_e32 v13, 1.0, v13
	v_add_f32_e32 v14, 1.0, v14
	v_add_f32_e32 v15, 1.0, v15
	v_rcp_f32_e32 v0, v0
	v_rcp_f32_e32 v1, v1
	v_rcp_f32_e32 v2, v2
	v_rcp_f32_e32 v3, v3
	v_rcp_f32_e32 v12, v12
	v_rcp_f32_e32 v13, v13
	v_rcp_f32_e32 v14, v14
	v_rcp_f32_e32 v15, v15
	v_pk_mul_f32 v[0:1], v[4:5], v[0:1]
	v_pk_mul_f32 v[2:3], v[6:7], v[2:3]
	v_pk_mul_f32 v[4:5], v[8:9], v[12:13]
	v_pk_mul_f32 v[6:7], v[10:11], v[14:15]
	s_and_saveexec_b64 s[4:5], vcc
	s_cbranch_execz .LBB0_278
	v_pk_mul_f32 v[8:9], v[0:1], v[0:1]
	v_pk_mul_f32 v[10:11], v[2:3], v[2:3]
	v_add_f32_e32 v8, v8, v9
	v_add_f32_e32 v8, v10, v8
	v_pk_mul_f32 v[12:13], v[4:5], v[4:5]
	v_add_f32_e32 v8, v11, v8
	v_and_b32_e32 v10, 64, v158
	v_add_f32_e32 v8, v12, v8
	v_xor_b32_e32 v9, 1, v158
	v_add_u32_e32 v10, 64, v10
	v_pk_mul_f32 v[14:15], v[6:7], v[6:7]
	v_add_f32_e32 v8, v13, v8
	v_cmp_lt_i32_e32 vcc, v9, v10
	v_add_f32_e32 v8, v14, v8
	v_add_f32_e32 v8, v15, v8
	v_cndmask_b32_e32 v9, v158, v9, vcc
	v_lshlrev_b32_e32 v9, 2, v9
	s_nop 1
	v_mov_b32_dpp v9, v8 quad_perm:[1,0,3,2] row_mask:0xf bank_mask:0xf
	v_add_f32_e32 v8, v8, v9
	v_xor_b32_e32 v9, 2, v158
	v_cmp_lt_i32_e32 vcc, v9, v10
	s_nop 1
	v_cndmask_b32_e32 v9, v158, v9, vcc
	v_lshlrev_b32_e32 v9, 2, v9
	s_nop 1
	v_mov_b32_dpp v9, v8 quad_perm:[2,3,0,1] row_mask:0xf bank_mask:0xf
	v_add_f32_e32 v8, v8, v9
	v_xor_b32_e32 v9, 4, v158
	v_cmp_lt_i32_e32 vcc, v9, v10
	s_nop 1
	v_cndmask_b32_e32 v9, v158, v9, vcc
	v_lshlrev_b32_e32 v9, 2, v9
	s_nop 1
	v_mov_b32_dpp v9, v8 row_half_mirror row_mask:0xf bank_mask:0xf
	v_add_f32_e32 v8, v8, v9
	v_xor_b32_e32 v9, 8, v158
	v_cmp_lt_i32_e32 vcc, v9, v10
	s_nop 1
	v_cndmask_b32_e32 v9, v158, v9, vcc
	v_lshlrev_b32_e32 v9, 2, v9
	s_nop 1
	v_mov_b32_dpp v9, v8 row_ror:8 row_mask:0xf bank_mask:0xf
	v_add_f32_e32 v8, v8, v9
	v_add_f32_e32 v8, 0x358637bd, v8
	v_mul_f32_e32 v9, 0x4b800000, v8
	v_cmp_gt_f32_e32 vcc, s46, v8
	s_nop 1
	v_cndmask_b32_e32 v8, v8, v9, vcc
	v_rsq_f32_e32 v8, v8
	s_nop 0
	v_mul_f32_e32 v9, 0x45800000, v8
	v_cndmask_b32_e32 v8, v8, v9, vcc
	v_mul_f32_e32 v8, v157, v8
	v_pk_mul_f32 v[6:7], v[6:7], v[8:9] op_sel_hi:[1,0]
	v_pk_mul_f32 v[4:5], v[4:5], v[8:9] op_sel_hi:[1,0]
	v_pk_mul_f32 v[2:3], v[2:3], v[8:9] op_sel_hi:[1,0]
	v_pk_mul_f32 v[0:1], v[0:1], v[8:9] op_sel_hi:[1,0]
	s_branch .LBB0_278
